# DeltaNet scan compute loops: U-prefetch vmcnt(0) waits moved from ~7 MFMAs into each step down to the first consumer of the loaded data
# baseline (speedup 1.0000x reference)
; #define MFMA32(a, b, c) __builtin_amdgcn_mfma_f32_32x32x16_bf16((a), (b), (c), 0, 0, 0)
; DI float bflo(unsigned w) { return __uint_as_float(w << 16); }
; DI float bfhi(unsigned w) { return __uint_as_float(w & 0xffff0000u); }
; DI void dn_scan_item(const Params& p, int seqbase, int T, int h, int dir, char* lds) {
;     ...
;     auto compute = [&](int n, int par, URegs& U) {
;         int lane = lane0; asm volatile("" : "+v"(lane));
;         const int r32 = lane & 31, hh = lane >> 5;
;         const char* buf = lds + par * SL_BUF;
;         f32x16 vn[2], o[2];
; #pragma unroll
;         for (int pt = 0; pt < 2; ++pt) {
;             const unsigned uu[8] = {U.un[pt][0].x, U.un[pt][0].y, U.un[pt][0].z, U.un[pt][0].w, U.un[pt][1].x, U.un[pt][1].y, U.un[pt][1].z, U.un[pt][1].w};
; #pragma unroll
;             for (int e = 0; e < 8; ++e) { vn[pt][2 * e] = bflo(uu[e]); vn[pt][2 * e + 1] = bfhi(uu[e]); }
; #pragma unroll
;             for (int i = 0; i < 16; ++i) o[pt][i] = 0.f;
;         }
;         const float gl = __expf(U.gl);
;         if (n + 2 < N) uload(n + 2, U);
; #pragma unroll
;         for (int ks = 0; ks < 8; ++ks) {
;             const bf16x8 sb = pack8(S[ks >> 1], ks & 1);
;             const int off = (ks * 16 + 4 * hh) * 2;
; #pragma unroll
;             for (int pt = 0; pt < 2; ++pt) {
;                 const char* wr = buf + SL_W + (pt * 32 + r32) * 264 + off;
;                 const char* qr = buf + SL_QG + (pt * 32 + r32) * 264 + off;
;                 vn[pt] = MFMA32(ld2x64(wr, wr + 16), sb, vn[pt]);
;                 o[pt] = MFMA32(ld2x64(qr, qr + 16), sb, o[pt]);
;             }
;         }
;         bf16x8 vb[4];
; #pragma unroll
;         for (int kp = 0; kp < 4; ++kp) vb[kp] = pack8(vn[kp >> 1], kp & 1);
; #pragma unroll
;         for (int d = 0; d < 4; ++d) S[d] = S[d] * gl;
.LBB0_606:
	v_lshlrev_b32_e32 v122, 16, v145
	v_and_b32_e32 v123, 0xffff0000, v145
	v_ashrrev_i32_e32 v145, 5, v64
	v_lshlrev_b32_e32 v124, 16, v146
	v_and_b32_e32 v125, 0xffff0000, v146
	v_lshlrev_b32_e32 v146, 3, v145
	v_and_b32_e32 v184, 31, v64
	v_add_u32_e32 v72, 0, v146
	v_mad_u32_u24 v68, v184, s88, v72
	v_lshlrev_b32_e32 v116, 16, v150
	v_and_b32_e32 v117, 0xffff0000, v150
	v_add_u32_e32 v150, 0xe800, v68
	v_lshlrev_b32_e32 v96, 16, v156
	v_and_b32_e32 v97, 0xffff0000, v156
	v_lshlrev_b32_e32 v98, 16, v157
	v_and_b32_e32 v99, 0xffff0000, v157
	v_lshlrev_b32_e32 v108, 16, v154
	v_and_b32_e32 v109, 0xffff0000, v154
	v_lshlrev_b32_e32 v110, 16, v155
	v_and_b32_e32 v111, 0xffff0000, v155
	ds_read2_b64 v[68:71], v150 offset0:64 offset1:66
	ds_read2_b64 v[154:157], v150 offset0:68 offset1:70
	v_mul_f32_e32 v64, 0x3fb8aa3b, v206
	v_add_u32_e32 v73, s90, v146
	v_lshlrev_b32_e32 v100, 16, v158
	v_and_b32_e32 v101, 0xffff0000, v158
	v_lshlrev_b32_e32 v102, 16, v159
	v_and_b32_e32 v103, 0xffff0000, v159
	v_lshlrev_b32_e32 v104, 16, v152
	v_and_b32_e32 v105, 0xffff0000, v152
	v_lshlrev_b32_e32 v106, 16, v153
	v_and_b32_e32 v107, 0xffff0000, v153
	v_lshlrev_b32_e32 v120, 16, v144
	v_and_b32_e32 v121, 0xffff0000, v144
	v_exp_f32_e32 v144, v64
	v_cvt_pk_bf16_f32 v64, v48, v49
	v_cvt_pk_bf16_f32 v65, v50, v51
	v_cvt_pk_bf16_f32 v66, v52, v53
	v_cvt_pk_bf16_f32 v67, v54, v55
	v_mad_u32_u24 v74, v184, s88, v73
	v_lshlrev_b32_e32 v126, 16, v147
	s_waitcnt lgkmcnt(1)
	v_mfma_f32_32x32x16_bf16 v[96:111], v[68:71], v[64:67], v[96:111]
	ds_read2_b64 v[68:71], v74 offset1:2
	v_and_b32_e32 v127, 0xffff0000, v147
	v_mad_u32_u24 v147, v184, s88, v179
	v_lshlrev_b32_e32 v118, 16, v151
	v_and_b32_e32 v119, 0xffff0000, v151
	v_lshlrev_b32_e32 v112, 16, v148
	v_and_b32_e32 v113, 0xffff0000, v148
	s_waitcnt lgkmcnt(0)
	v_mfma_f32_32x32x16_bf16 v[80:95], v[68:71], v[64:67], 0
	v_add_u32_e32 v68, v72, v147
	v_add_u32_e32 v151, 0xe800, v68
	ds_read2_b64 v[68:71], v151 offset0:64 offset1:66
	ds_read2_b64 v[208:211], v151 offset0:68 offset1:70
	v_mov_b32_e32 v148, s90
	v_lshlrev_b32_e32 v114, 16, v149
	v_and_b32_e32 v115, 0xffff0000, v149
	v_add_u32_e32 v149, 32, v146
	v_mad_u32_u24 v153, v184, s88, v148
	v_cvt_pk_bf16_f32 v212, v56, v57
	v_cvt_pk_bf16_f32 v213, v58, v59
	v_cvt_pk_bf16_f32 v214, v60, v61
	v_cvt_pk_bf16_f32 v215, v62, v63
	v_add_u32_e32 v148, v153, v149
	v_add_u32_e32 v72, v73, v147
	v_mfma_f32_32x32x16_bf16 v[96:111], v[154:157], v[212:215], v[96:111]
	ds_read2_b64 v[154:157], v148 offset1:2
	v_add_u32_e32 v152, s90, v147
	v_add_u32_e32 v147, v152, v149
	v_mul_f32_e64 v62, v144, v62
	v_mul_f32_e64 v63, v144, v63
	v_pk_mul_f32 v[60:61], v[144:145], v[60:61] op_sel_hi:[0,1]
	v_pk_mul_f32 v[58:59], v[144:145], v[58:59] op_sel_hi:[0,1]
	v_pk_mul_f32 v[56:57], v[144:145], v[56:57] op_sel_hi:[0,1]
	s_waitcnt lgkmcnt(2)
	v_mfma_f32_32x32x16_bf16 v[112:127], v[68:71], v[64:67], v[112:127]
	ds_read2_b64 v[68:71], v72 offset1:2
	v_mul_f32_e64 v54, v144, v54
	v_mul_f32_e64 v55, v144, v55
	v_mul_f32_e64 v52, v144, v52
	v_mul_f32_e64 v53, v144, v53
	v_pk_mul_f32 v[50:51], v[144:145], v[50:51] op_sel_hi:[0,1]
	v_pk_mul_f32 v[48:49], v[144:145], v[48:49] op_sel_hi:[0,1]
	s_xor_b32 s23, s22, -2
	s_add_i32 s12, s16, -2
	s_waitcnt lgkmcnt(1)
	v_mfma_f32_32x32x16_bf16 v[80:95], v[154:157], v[212:215], v[80:95]
	ds_read2_b64 v[154:157], v147 offset1:2
	v_add_u32_e32 v147, 64, v146
	v_add_u32_e32 v148, v153, v147
	s_add_i32 s23, s23, 32
	s_and_b64 s[24:25], s[2:3], exec
	s_cselect_b32 s12, s12, s23
	s_add_i32 s24, s12, s27
	s_waitcnt lgkmcnt(1)
	v_mfma_f32_32x32x16_bf16 v[64:79], v[68:71], v[64:67], 0
	s_ashr_i32 s25, s24, 31
	s_lshl_b64 s[24:25], s[24:25], 16
	s_add_u32 s24, s19, s24
	s_addc_u32 s25, s20, s25
	s_add_i32 s16, s16, 2
	s_add_i32 s15, s15, -2
	s_cmp_gt_u32 s22, 29
	v_mfma_f32_32x32x16_bf16 v[112:127], v[208:211], v[212:215], v[112:127]
	ds_read2_b64 v[208:211], v150 offset0:72 offset1:74
	s_waitcnt lgkmcnt(1)
	v_mfma_f32_32x32x16_bf16 v[64:79], v[154:157], v[212:215], v[64:79]
	v_cvt_pk_bf16_f32 v154, v32, v33
	v_cvt_pk_bf16_f32 v155, v34, v35
	v_cvt_pk_bf16_f32 v156, v36, v37
	v_cvt_pk_bf16_f32 v157, v38, v39
	v_mul_f32_e64 v38, v144, v38
	v_mul_f32_e64 v39, v144, v39
	v_pk_mul_f32 v[36:37], v[144:145], v[36:37] op_sel_hi:[0,1]
	v_pk_mul_f32 v[34:35], v[144:145], v[34:35] op_sel_hi:[0,1]
	s_waitcnt lgkmcnt(0)
	v_mfma_f32_32x32x16_bf16 v[96:111], v[208:211], v[154:157], v[96:111]
	ds_read2_b64 v[208:211], v148 offset1:2
	v_add_u32_e32 v148, v152, v147
	v_mul_f32_e64 v32, v144, v32
	v_mul_f32_e64 v33, v144, v33
	s_waitcnt lgkmcnt(0)
	v_mfma_f32_32x32x16_bf16 v[80:95], v[208:211], v[154:157], v[80:95]
	ds_read2_b64 v[208:211], v151 offset0:72 offset1:74
	s_waitcnt lgkmcnt(0)
	v_mfma_f32_32x32x16_bf16 v[112:127], v[208:211], v[154:157], v[112:127]
	ds_read2_b64 v[208:211], v148 offset1:2
	v_add_u32_e32 v148, 0x60, v146
	v_add_u32_e32 v158, v153, v148
	s_waitcnt lgkmcnt(0)
	v_mfma_f32_32x32x16_bf16 v[64:79], v[208:211], v[154:157], v[64:79]
	ds_read2_b64 v[208:211], v150 offset0:76 offset1:78
	v_cvt_pk_bf16_f32 v154, v40, v41
	v_cvt_pk_bf16_f32 v155, v42, v43
	v_cvt_pk_bf16_f32 v156, v44, v45
	v_cvt_pk_bf16_f32 v157, v46, v47
	v_pk_mul_f32 v[46:47], v[144:145], v[46:47] op_sel_hi:[0,1]
	v_pk_mul_f32 v[44:45], v[144:145], v[44:45] op_sel_hi:[0,1]
	s_waitcnt lgkmcnt(0)
	v_mfma_f32_32x32x16_bf16 v[96:111], v[208:211], v[154:157], v[96:111]
	ds_read2_b64 v[208:211], v158 offset1:2
	v_add_u32_e32 v158, v152, v148
	v_mul_f32_e64 v42, v144, v42
	v_mul_f32_e64 v43, v144, v43
	v_mul_f32_e64 v40, v144, v40
	v_mul_f32_e64 v41, v144, v41
	s_waitcnt lgkmcnt(0)
; #define MFMA32(a, b, c) __builtin_amdgcn_mfma_f32_32x32x16_bf16((a), (b), (c), 0, 0, 0)
; DI void dn_scan_item(const Params& p, int seqbase, int T, int h, int dir, char* lds) {
;     ...
;         for (int ks = 0; ks < 8; ++ks) {
;             const bf16x8 sb = pack8(S[ks >> 1], ks & 1);
;             const int off = (ks * 16 + 4 * hh) * 2;
; #pragma unroll
;             for (int pt = 0; pt < 2; ++pt) {
;                 const char* wr = buf + SL_W + (pt * 32 + r32) * 264 + off;
;                 const char* qr = buf + SL_QG + (pt * 32 + r32) * 264 + off;
;                 vn[pt] = MFMA32(ld2x64(wr, wr + 16), sb, vn[pt]);
;                 o[pt] = MFMA32(ld2x64(qr, qr + 16), sb, o[pt]);
;             }
;         }
;         bf16x8 vb[4];
; #pragma unroll
;         for (int kp = 0; kp < 4; ++kp) vb[kp] = pack8(vn[kp >> 1], kp & 1);
; #pragma unroll
;         for (int d = 0; d < 4; ++d) S[d] = S[d] * gl;
; #pragma unroll
;         for (int kp = 0; kp < 4; ++kp) {
;             const int off = (kp * 16 + 4 * hh) * 2;
; #pragma unroll
;             for (int pt = 0; pt < 2; ++pt) { const char* ar = buf + SL_AT + (pt * 32 + r32) * 136 + off; o[pt] = MFMA32(ld2x64(ar, ar + 16), vb[kp], o[pt]); }
; #pragma unroll
;             for (int d = 0; d < 4; ++d) { const char* kr = buf + SL_KDT + (d * 32 + r32) * 136 + off; S[d] = MFMA32(ld2x64(kr, kr + 16), vb[kp], S[d]); }
	v_mfma_f32_32x32x16_bf16 v[80:95], v[208:211], v[154:157], v[80:95]
	ds_read2_b64 v[208:211], v151 offset0:76 offset1:78
	s_waitcnt lgkmcnt(0)
	v_mfma_f32_32x32x16_bf16 v[112:127], v[208:211], v[154:157], v[112:127]
	ds_read2_b64 v[208:211], v158 offset1:2
	v_add_u32_e32 v158, 0x80, v146
	v_add_u32_e32 v159, v153, v158
	v_add_u32_e32 v158, v152, v158
	s_waitcnt lgkmcnt(0)
	v_mfma_f32_32x32x16_bf16 v[64:79], v[208:211], v[154:157], v[64:79]
	ds_read2_b64 v[208:211], v150 offset0:80 offset1:82
	v_cvt_pk_bf16_f32 v154, v16, v17
	v_cvt_pk_bf16_f32 v155, v18, v19
	v_cvt_pk_bf16_f32 v156, v20, v21
	v_cvt_pk_bf16_f32 v157, v22, v23
	v_pk_mul_f32 v[22:23], v[144:145], v[22:23] op_sel_hi:[0,1]
	v_pk_mul_f32 v[20:21], v[144:145], v[20:21] op_sel_hi:[0,1]
	s_waitcnt lgkmcnt(0)
	v_mfma_f32_32x32x16_bf16 v[96:111], v[208:211], v[154:157], v[96:111]
	ds_read2_b64 v[208:211], v159 offset1:2
	v_mul_f32_e64 v18, v144, v18
	v_mul_f32_e64 v19, v144, v19
	v_mul_f32_e64 v16, v144, v16
	v_mul_f32_e64 v17, v144, v17
	s_waitcnt lgkmcnt(0)
	v_mfma_f32_32x32x16_bf16 v[80:95], v[208:211], v[154:157], v[80:95]
	ds_read2_b64 v[208:211], v151 offset0:80 offset1:82
	s_waitcnt lgkmcnt(0)
	v_mfma_f32_32x32x16_bf16 v[112:127], v[208:211], v[154:157], v[112:127]
	ds_read2_b64 v[208:211], v158 offset1:2
	v_add_u32_e32 v158, 0xa0, v146
	v_add_u32_e32 v159, v153, v158
	v_add_u32_e32 v158, v152, v158
	s_waitcnt lgkmcnt(0)
	v_mfma_f32_32x32x16_bf16 v[64:79], v[208:211], v[154:157], v[64:79]
	ds_read2_b64 v[208:211], v150 offset0:84 offset1:86
	v_cvt_pk_bf16_f32 v154, v24, v25
	v_cvt_pk_bf16_f32 v155, v26, v27
	v_cvt_pk_bf16_f32 v156, v28, v29
	v_cvt_pk_bf16_f32 v157, v30, v31
	v_pk_mul_f32 v[30:31], v[144:145], v[30:31] op_sel_hi:[0,1]
	v_pk_mul_f32 v[28:29], v[144:145], v[28:29] op_sel_hi:[0,1]
	s_waitcnt lgkmcnt(0)
	v_mfma_f32_32x32x16_bf16 v[96:111], v[208:211], v[154:157], v[96:111]
	ds_read2_b64 v[208:211], v159 offset1:2
	v_mul_f32_e64 v26, v144, v26
	v_mul_f32_e64 v27, v144, v27
	v_mul_f32_e64 v24, v144, v24
	v_mul_f32_e64 v25, v144, v25
	s_waitcnt lgkmcnt(0)
	v_mfma_f32_32x32x16_bf16 v[80:95], v[208:211], v[154:157], v[80:95]
	ds_read2_b64 v[208:211], v151 offset0:84 offset1:86
	s_waitcnt lgkmcnt(0)
	v_mfma_f32_32x32x16_bf16 v[112:127], v[208:211], v[154:157], v[112:127]
	ds_read2_b64 v[208:211], v158 offset1:2
	v_add_u32_e32 v158, 0xc0, v146
	v_add_u32_e32 v159, v153, v158
	v_add_u32_e32 v158, v152, v158
	s_waitcnt lgkmcnt(0)
	v_mfma_f32_32x32x16_bf16 v[64:79], v[208:211], v[154:157], v[64:79]
	ds_read2_b64 v[208:211], v150 offset0:88 offset1:90
	v_cvt_pk_bf16_f32 v154, v0, v1
	v_cvt_pk_bf16_f32 v155, v2, v3
	v_cvt_pk_bf16_f32 v156, v4, v5
	v_cvt_pk_bf16_f32 v157, v6, v7
	v_pk_mul_f32 v[6:7], v[144:145], v[6:7] op_sel_hi:[0,1]
	v_pk_mul_f32 v[4:5], v[144:145], v[4:5] op_sel_hi:[0,1]
	s_waitcnt lgkmcnt(0)
	v_mfma_f32_32x32x16_bf16 v[96:111], v[208:211], v[154:157], v[96:111]
	ds_read2_b64 v[208:211], v159 offset1:2
	v_mul_f32_e64 v2, v144, v2
	v_mul_f32_e64 v3, v144, v3
	v_mul_f32_e64 v0, v144, v0
	v_mul_f32_e64 v1, v144, v1
	s_waitcnt lgkmcnt(0)
	v_mfma_f32_32x32x16_bf16 v[80:95], v[208:211], v[154:157], v[80:95]
	ds_read2_b64 v[208:211], v151 offset0:88 offset1:90
	s_waitcnt lgkmcnt(0)
	v_mfma_f32_32x32x16_bf16 v[112:127], v[208:211], v[154:157], v[112:127]
	ds_read2_b64 v[208:211], v158 offset1:2
	v_add_u32_e32 v158, 0xe0, v146
	v_add_u32_e32 v153, v153, v158
	v_add_u32_e32 v158, v152, v158
	s_waitcnt lgkmcnt(0)
	v_mfma_f32_32x32x16_bf16 v[64:79], v[208:211], v[154:157], v[64:79]
	ds_read2_b64 v[208:211], v150 offset0:92 offset1:94
	v_cvt_pk_bf16_f32 v154, v8, v9
	v_cvt_pk_bf16_f32 v155, v10, v11
	v_cvt_pk_bf16_f32 v156, v12, v13
	v_cvt_pk_bf16_f32 v157, v14, v15
	v_pk_mul_f32 v[14:15], v[144:145], v[14:15] op_sel_hi:[0,1]
	v_pk_mul_f32 v[12:13], v[144:145], v[12:13] op_sel_hi:[0,1]
	s_waitcnt lgkmcnt(0)
	v_mfma_f32_32x32x16_bf16 v[96:111], v[208:211], v[154:157], v[96:111]
	ds_read2_b64 v[208:211], v153 offset1:2
	ds_read2_b64 v[150:153], v151 offset0:92 offset1:94
	v_mul_f32_e64 v10, v144, v10
	v_mul_f32_e64 v11, v144, v11
	v_mul_f32_e64 v8, v144, v8
	v_mul_f32_e64 v9, v144, v9
	s_nop 5
	v_cvt_pk_bf16_f32 v104, v104, v105
	s_waitcnt lgkmcnt(0)
	v_mfma_f32_32x32x16_bf16 v[112:127], v[150:153], v[154:157], v[112:127]
	ds_read2_b64 v[150:153], v158 offset1:2
	v_cvt_pk_bf16_f32 v105, v106, v107
	v_cvt_pk_bf16_f32 v106, v108, v109
	v_cvt_pk_bf16_f32 v107, v110, v111
	s_waitcnt lgkmcnt(0)
	v_mfma_f32_32x32x16_bf16 v[64:79], v[150:153], v[154:157], v[64:79]
	v_cvt_pk_bf16_f32 v152, v100, v101
	s_nop 4
	v_cvt_pk_bf16_f32 v100, v112, v113
	v_add_u32_e32 v113, s91, v146
	v_mad_u32_u24 v108, v184, s89, v113
	ds_read2_b64 v[108:111], v108 offset1:2
	v_cvt_pk_bf16_f32 v150, v96, v97
	v_cvt_pk_bf16_f32 v151, v98, v99
	v_mfma_f32_32x32x16_bf16 v[80:95], v[208:211], v[154:157], v[80:95]
	v_cvt_pk_bf16_f32 v153, v102, v103
	v_cvt_pk_bf16_f32 v101, v114, v115
	v_mad_u32_u24 v114, v184, s89, v181
	v_cvt_pk_bf16_f32 v102, v116, v117
	v_mul_u32_u24_e32 v112, 0x88, v184
	v_add3_u32 v117, s92, v149, v112
	v_cvt_pk_bf16_f32 v103, v118, v119
	s_waitcnt lgkmcnt(0)
	v_mfma_f32_32x32x16_bf16 v[80:95], v[108:111], v[150:153], v[80:95]
	v_add_u32_e32 v108, v113, v114
	ds_read2_b64 v[108:111], v108 offset1:2
	v_add_u32_e32 v113, s92, v146
	v_mad_u32_u24 v115, v184, s89, v113
	v_cvt_pk_bf16_f32 v96, v120, v121
	v_cvt_pk_bf16_f32 v97, v122, v123
	v_cvt_pk_bf16_f32 v98, v124, v125
	s_waitcnt lgkmcnt(0)
	v_mfma_f32_32x32x16_bf16 v[64:79], v[108:111], v[150:153], v[64:79]
	ds_read2_b64 v[108:111], v115 offset1:2
	v_cvt_pk_bf16_f32 v99, v126, v127
	s_waitcnt vmcnt(0)
; #define MFMA32(a, b, c) __builtin_amdgcn_mfma_f32_32x32x16_bf16((a), (b), (c), 0, 0, 0)
; DI void dn_scan_item(const Params& p, int seqbase, int T, int h, int dir, char* lds) {
;     ...
;         for (int kp = 0; kp < 4; ++kp) {
;             const int off = (kp * 16 + 4 * hh) * 2;
; #pragma unroll
;             for (int pt = 0; pt < 2; ++pt) { const char* ar = buf + SL_AT + (pt * 32 + r32) * 136 + off; o[pt] = MFMA32(ld2x64(ar, ar + 16), vb[kp], o[pt]); }
; #pragma unroll
;             for (int d = 0; d < 4; ++d) { const char* kr = buf + SL_KDT + (d * 32 + r32) * 136 + off; S[d] = MFMA32(ld2x64(kr, kr + 16), vb[kp], S[d]); }
;         }
	v_mov_b32_e32 v206, v207
	v_mov_b64_e32 v[156:157], v[164:165]
	v_mov_b64_e32 v[158:159], v[166:167]
	s_waitcnt lgkmcnt(0)
	v_mfma_f32_32x32x16_bf16 v[48:63], v[108:111], v[150:153], v[48:63]
	v_add_u32_e32 v108, v113, v114
	ds_read2_b64 v[108:111], v108 offset1:2
	s_waitcnt lgkmcnt(0)
	v_mfma_f32_32x32x16_bf16 v[32:47], v[108:111], v[150:153], v[32:47]
	v_add_u32_e32 v108, 0x2000, v115
	ds_read2_b64 v[108:111], v108 offset0:64 offset1:66
	s_waitcnt lgkmcnt(0)
	v_mfma_f32_32x32x16_bf16 v[16:31], v[108:111], v[150:153], v[16:31]
	v_add_u32_e32 v108, 0x3000, v115
	ds_read2_b64 v[108:111], v108 offset0:96 offset1:98
	v_add_u32_e32 v115, s91, v114
	v_add_u32_e32 v114, s92, v114
	s_waitcnt lgkmcnt(0)
	v_mfma_f32_32x32x16_bf16 v[0:15], v[108:111], v[150:153], v[0:15]
	v_mov_b32_e32 v108, s91
	v_mad_u32_u24 v113, v184, s89, v108
	v_add_u32_e32 v108, v113, v149
	ds_read2_b64 v[108:111], v108 offset1:2
	v_mov_b64_e32 v[152:153], v[160:161]
	v_mov_b64_e32 v[154:155], v[162:163]
	s_waitcnt lgkmcnt(0)
	v_mfma_f32_32x32x16_bf16 v[80:95], v[108:111], v[104:107], v[80:95]
	v_add_u32_e32 v108, v115, v149
	ds_read2_b64 v[108:111], v108 offset1:2
	s_waitcnt lgkmcnt(0)
	v_mfma_f32_32x32x16_bf16 v[64:79], v[108:111], v[104:107], v[64:79]
	v_mov_b32_e32 v108, s92
	v_mad_u32_u24 v116, v184, s89, v108
	v_add_u32_e32 v108, v116, v149
	ds_read2_b64 v[108:111], v108 offset1:2
	v_lshlrev_b32_e32 v184, 1, v184
	s_waitcnt lgkmcnt(0)
	v_mfma_f32_32x32x16_bf16 v[48:63], v[108:111], v[104:107], v[48:63]
	v_add_u32_e32 v108, v114, v149
	ds_read2_b64 v[108:111], v108 offset1:2
	s_waitcnt lgkmcnt(0)
	v_mfma_f32_32x32x16_bf16 v[32:47], v[108:111], v[104:107], v[32:47]
	v_add_u32_e32 v108, 0x2000, v117
	ds_read2_b64 v[108:111], v108 offset0:64 offset1:66
	s_waitcnt lgkmcnt(0)
	v_mfma_f32_32x32x16_bf16 v[16:31], v[108:111], v[104:107], v[16:31]
	v_add_u32_e32 v108, 0x3000, v117
	ds_read2_b64 v[108:111], v108 offset0:96 offset1:98
	s_waitcnt lgkmcnt(0)
	v_mfma_f32_32x32x16_bf16 v[0:15], v[108:111], v[104:107], v[0:15]
	v_add_u32_e32 v104, v113, v147
	ds_read2_b64 v[104:107], v104 offset1:2
	v_add3_u32 v108, s92, v147, v112
	s_waitcnt lgkmcnt(0)
	v_mfma_f32_32x32x16_bf16 v[80:95], v[104:107], v[100:103], v[80:95]
	v_add_u32_e32 v104, v115, v147
	ds_read2_b64 v[104:107], v104 offset1:2
	s_waitcnt lgkmcnt(0)
	v_mfma_f32_32x32x16_bf16 v[64:79], v[104:107], v[100:103], v[64:79]
	v_add_u32_e32 v104, v116, v147
	ds_read2_b64 v[104:107], v104 offset1:2
	s_waitcnt lgkmcnt(0)
	v_mfma_f32_32x32x16_bf16 v[48:63], v[104:107], v[100:103], v[48:63]
	v_add_u32_e32 v104, v114, v147
	ds_read2_b64 v[104:107], v104 offset1:2
	s_waitcnt lgkmcnt(0)
	v_mfma_f32_32x32x16_bf16 v[32:47], v[104:107], v[100:103], v[32:47]
	v_add_u32_e32 v104, 0x2000, v108
	ds_read2_b64 v[104:107], v104 offset0:64 offset1:66
	s_waitcnt lgkmcnt(0)
	v_mfma_f32_32x32x16_bf16 v[16:31], v[104:107], v[100:103], v[16:31]
	v_add_u32_e32 v104, 0x3000, v108
	ds_read2_b64 v[104:107], v104 offset0:96 offset1:98
	s_waitcnt lgkmcnt(0)
	v_mfma_f32_32x32x16_bf16 v[0:15], v[104:107], v[100:103], v[0:15]
	v_add_u32_e32 v100, v113, v148
	ds_read2_b64 v[100:103], v100 offset1:2
	v_add3_u32 v104, s92, v148, v112
	s_waitcnt lgkmcnt(0)
	v_mfma_f32_32x32x16_bf16 v[80:95], v[100:103], v[96:99], v[80:95]
	v_add_u32_e32 v100, v115, v148
	ds_read2_b64 v[100:103], v100 offset1:2
	s_nop 9
	v_cvt_pk_bf16_f32 v80, v80, s0
	s_waitcnt lgkmcnt(0)
	v_mfma_f32_32x32x16_bf16 v[64:79], v[100:103], v[96:99], v[64:79]
	v_add_u32_e32 v100, v116, v148
	ds_read2_b64 v[100:103], v100 offset1:2
	v_cvt_pk_bf16_f32 v82, v82, s0
	s_nop 8
	v_cvt_pk_bf16_f32 v64, v64, s0
	s_waitcnt lgkmcnt(0)
	v_mfma_f32_32x32x16_bf16 v[48:63], v[100:103], v[96:99], v[48:63]
	v_add_u32_e32 v100, v114, v148
	ds_read2_b64 v[100:103], v100 offset1:2
	v_cvt_pk_bf16_f32 v66, v66, s0
	v_mov_b64_e32 v[148:149], v[172:173]
	v_mov_b64_e32 v[150:151], v[174:175]
	s_waitcnt lgkmcnt(0)
	v_mfma_f32_32x32x16_bf16 v[32:47], v[100:103], v[96:99], v[32:47]
	v_add_u32_e32 v100, 0x2000, v104
	ds_read2_b64 v[100:103], v100 offset0:64 offset1:66
	s_waitcnt lgkmcnt(0)
	v_mfma_f32_32x32x16_bf16 v[16:31], v[100:103], v[96:99], v[16:31]
	v_add_u32_e32 v100, 0x3000, v104
	ds_read2_b64 v[100:103], v100 offset0:96 offset1:98
	s_waitcnt lgkmcnt(0)
; DI bf16_t f2bf(float x) { return (bf16_t)(cvtpk(x, 0.f) & 0xffffu); }
; DI int crow(int r, int hi) { return (r & 3) + 8 * (r >> 2) + 4 * hi; }
; DI void dn_scan_item(const Params& p, int seqbase, int T, int h, int dir, char* lds) {
;     ...
;         const int cn = dir ? N - 1 - n : n; const size_t mrow0 = (size_t)(gch0 + cn) * 64;
; #pragma unroll
;         for (int pt = 0; pt < 2; ++pt)
; #pragma unroll
;             for (int i = 0; i < 16; ++i) {
;                 const int pi = pt * 32 + crow(i, hh), tl = dir ? 63 - pi : pi;
;                 Oout[(mrow0 + tl) * 512 + h * 128 + slab * 32 + r32] = f2bf(o[pt][i]);
;             }
	v_mfma_f32_32x32x16_bf16 v[0:15], v[100:103], v[96:99], v[0:15]
	v_lshlrev_b32_e32 v100, 2, v145
	v_sub_u32_e32 v98, 63, v100
	v_cndmask_b32_e64 v98, v98, v100, s[2:3]
	v_ashrrev_i32_e32 v99, 31, v98
	v_lshl_add_u64 v[96:97], s[24:25], 0, v[184:185]
	v_lshlrev_b64 v[98:99], 10, v[98:99]
	v_lshl_add_u64 v[98:99], v[96:97], 0, v[98:99]
	global_store_short v[98:99], v80, off
	v_or_b32_e32 v80, 1, v100
	v_sub_u32_e32 v98, 63, v80
	v_cndmask_b32_e64 v80, v98, v80, s[2:3]
	v_cvt_pk_bf16_f32 v98, v81, s0
	v_ashrrev_i32_e32 v81, 31, v80
	v_lshlrev_b64 v[80:81], 10, v[80:81]
	v_lshl_add_u64 v[80:81], v[96:97], 0, v[80:81]
	global_store_short v[80:81], v98, off
	v_or_b32_e32 v80, 2, v100
	v_sub_u32_e32 v81, 63, v80
	v_cndmask_b32_e64 v80, v81, v80, s[2:3]
	v_ashrrev_i32_e32 v81, 31, v80
	v_lshlrev_b64 v[80:81], 10, v[80:81]
	v_lshl_add_u64 v[80:81], v[96:97], 0, v[80:81]
	global_store_short v[80:81], v82, off
	v_or_b32_e32 v80, 3, v100
	v_sub_u32_e32 v81, 63, v80
	v_cndmask_b32_e64 v80, v81, v80, s[2:3]
	v_ashrrev_i32_e32 v81, 31, v80
	v_lshlrev_b64 v[80:81], 10, v[80:81]
	v_cvt_pk_bf16_f32 v82, v83, s0
	v_lshl_add_u64 v[80:81], v[96:97], 0, v[80:81]
	global_store_short v[80:81], v82, off
	v_add_u32_e32 v80, 8, v100
	v_sub_u32_e32 v81, 55, v100
	v_cndmask_b32_e64 v80, v81, v80, s[2:3]
	v_ashrrev_i32_e32 v81, 31, v80
	v_lshlrev_b64 v[80:81], 10, v[80:81]
	v_cvt_pk_bf16_f32 v82, v84, s0
	v_lshl_add_u64 v[80:81], v[96:97], 0, v[80:81]
	global_store_short v[80:81], v82, off
	v_add_u32_e32 v80, 9, v100
	v_sub_u32_e32 v81, 54, v100
	v_cndmask_b32_e64 v80, v81, v80, s[2:3]
	v_ashrrev_i32_e32 v81, 31, v80
	v_lshlrev_b64 v[80:81], 10, v[80:81]
	v_cvt_pk_bf16_f32 v82, v85, s0
	v_lshl_add_u64 v[80:81], v[96:97], 0, v[80:81]
	global_store_short v[80:81], v82, off
	v_add_u32_e32 v80, 10, v100
	v_sub_u32_e32 v81, 53, v100
	v_cndmask_b32_e64 v80, v81, v80, s[2:3]
	v_ashrrev_i32_e32 v81, 31, v80
	v_lshlrev_b64 v[80:81], 10, v[80:81]
	v_cvt_pk_bf16_f32 v82, v86, s0
	v_lshl_add_u64 v[80:81], v[96:97], 0, v[80:81]
	global_store_short v[80:81], v82, off
	v_add_u32_e32 v80, 11, v100
	v_sub_u32_e32 v81, 52, v100
	v_cndmask_b32_e64 v80, v81, v80, s[2:3]
	v_ashrrev_i32_e32 v81, 31, v80
	v_lshlrev_b64 v[80:81], 10, v[80:81]
	v_cvt_pk_bf16_f32 v82, v87, s0
	v_lshl_add_u64 v[80:81], v[96:97], 0, v[80:81]
	global_store_short v[80:81], v82, off
	v_add_u32_e32 v80, 16, v100
	v_sub_u32_e32 v81, 47, v100
	v_cndmask_b32_e64 v80, v81, v80, s[2:3]
	v_ashrrev_i32_e32 v81, 31, v80
	v_lshlrev_b64 v[80:81], 10, v[80:81]
	v_cvt_pk_bf16_f32 v82, v88, s0
	v_lshl_add_u64 v[80:81], v[96:97], 0, v[80:81]
	global_store_short v[80:81], v82, off
	v_add_u32_e32 v80, 17, v100
	v_sub_u32_e32 v81, 46, v100
	v_cndmask_b32_e64 v80, v81, v80, s[2:3]
	v_ashrrev_i32_e32 v81, 31, v80
	v_lshlrev_b64 v[80:81], 10, v[80:81]
	v_cvt_pk_bf16_f32 v82, v89, s0
	v_lshl_add_u64 v[80:81], v[96:97], 0, v[80:81]
	global_store_short v[80:81], v82, off
	v_add_u32_e32 v80, 18, v100
	v_sub_u32_e32 v81, 45, v100
	v_cndmask_b32_e64 v80, v81, v80, s[2:3]
	v_ashrrev_i32_e32 v81, 31, v80
	v_lshlrev_b64 v[80:81], 10, v[80:81]
	v_cvt_pk_bf16_f32 v82, v90, s0
	v_lshl_add_u64 v[80:81], v[96:97], 0, v[80:81]
	global_store_short v[80:81], v82, off
	v_add_u32_e32 v80, 19, v100
	v_sub_u32_e32 v81, 44, v100
	v_cndmask_b32_e64 v80, v81, v80, s[2:3]
	v_ashrrev_i32_e32 v81, 31, v80
	v_lshlrev_b64 v[80:81], 10, v[80:81]
	v_cvt_pk_bf16_f32 v82, v91, s0
	v_lshl_add_u64 v[80:81], v[96:97], 0, v[80:81]
	global_store_short v[80:81], v82, off
	v_add_u32_e32 v80, 24, v100
	v_sub_u32_e32 v81, 39, v100
	v_cndmask_b32_e64 v80, v81, v80, s[2:3]
	v_ashrrev_i32_e32 v81, 31, v80
	v_lshlrev_b64 v[80:81], 10, v[80:81]
	v_cvt_pk_bf16_f32 v82, v92, s0
	v_lshl_add_u64 v[80:81], v[96:97], 0, v[80:81]
	global_store_short v[80:81], v82, off
	v_add_u32_e32 v80, 25, v100
	v_sub_u32_e32 v81, 38, v100
	v_cndmask_b32_e64 v80, v81, v80, s[2:3]
	v_ashrrev_i32_e32 v81, 31, v80
	v_lshlrev_b64 v[80:81], 10, v[80:81]
	v_cvt_pk_bf16_f32 v82, v93, s0
	v_lshl_add_u64 v[80:81], v[96:97], 0, v[80:81]
	global_store_short v[80:81], v82, off
	v_add_u32_e32 v80, 26, v100
	v_sub_u32_e32 v81, 37, v100
	v_cndmask_b32_e64 v80, v81, v80, s[2:3]
	v_ashrrev_i32_e32 v81, 31, v80
	v_lshlrev_b64 v[80:81], 10, v[80:81]
	v_cvt_pk_bf16_f32 v82, v94, s0
	v_lshl_add_u64 v[80:81], v[96:97], 0, v[80:81]
	global_store_short v[80:81], v82, off
	v_add_u32_e32 v80, 27, v100
	v_sub_u32_e32 v81, 36, v100
	v_cndmask_b32_e64 v80, v81, v80, s[2:3]
	v_ashrrev_i32_e32 v81, 31, v80
	v_lshlrev_b64 v[80:81], 10, v[80:81]
	v_cvt_pk_bf16_f32 v82, v95, s0
	v_lshl_add_u64 v[80:81], v[96:97], 0, v[80:81]
	global_store_short v[80:81], v82, off
	v_add_u32_e32 v80, 32, v100
	v_sub_u32_e32 v81, 31, v100
	v_cndmask_b32_e64 v80, v81, v80, s[2:3]
	v_ashrrev_i32_e32 v81, 31, v80
	v_lshlrev_b64 v[80:81], 10, v[80:81]
; DI bf16_t f2bf(float x) { return (bf16_t)(cvtpk(x, 0.f) & 0xffffu); }
; DI int crow(int r, int hi) { return (r & 3) + 8 * (r >> 2) + 4 * hi; }
; DI void dn_scan_item(const Params& p, int seqbase, int T, int h, int dir, char* lds) {
;     ...
;         const int cn = dir ? N - 1 - n : n; const size_t mrow0 = (size_t)(gch0 + cn) * 64;
; #pragma unroll
;         for (int pt = 0; pt < 2; ++pt)
; #pragma unroll
;             for (int i = 0; i < 16; ++i) {
;                 const int pi = pt * 32 + crow(i, hh), tl = dir ? 63 - pi : pi;
;                 Oout[(mrow0 + tl) * 512 + h * 128 + slab * 32 + r32] = f2bf(o[pt][i]);
;             }
;     ...
;         for (int n = 0; n < N; n += 2) {
;             compute(n, 0, UA);
;             __syncthreads();
;             compute(n + 1, 1, UB);
;             __syncthreads();
;         }
	v_lshl_add_u64 v[80:81], v[96:97], 0, v[80:81]
	global_store_short v[80:81], v64, off
	v_add_u32_e32 v64, 33, v100
	v_sub_u32_e32 v80, 30, v100
	v_cndmask_b32_e64 v64, v80, v64, s[2:3]
	v_cvt_pk_bf16_f32 v80, v65, s0
	v_ashrrev_i32_e32 v65, 31, v64
	v_lshlrev_b64 v[64:65], 10, v[64:65]
	v_lshl_add_u64 v[64:65], v[96:97], 0, v[64:65]
	global_store_short v[64:65], v80, off
	v_add_u32_e32 v64, 34, v100
	v_sub_u32_e32 v65, 29, v100
	v_cndmask_b32_e64 v64, v65, v64, s[2:3]
	v_ashrrev_i32_e32 v65, 31, v64
	v_lshlrev_b64 v[64:65], 10, v[64:65]
	v_lshl_add_u64 v[64:65], v[96:97], 0, v[64:65]
	global_store_short v[64:65], v66, off
	v_add_u32_e32 v64, 35, v100
	v_sub_u32_e32 v65, 28, v100
	v_cndmask_b32_e64 v64, v65, v64, s[2:3]
	v_ashrrev_i32_e32 v65, 31, v64
	v_lshlrev_b64 v[64:65], 10, v[64:65]
	v_cvt_pk_bf16_f32 v66, v67, s0
	v_lshl_add_u64 v[64:65], v[96:97], 0, v[64:65]
	global_store_short v[64:65], v66, off
	v_add_u32_e32 v64, 40, v100
	v_sub_u32_e32 v65, 23, v100
	v_cndmask_b32_e64 v64, v65, v64, s[2:3]
	v_ashrrev_i32_e32 v65, 31, v64
	v_lshlrev_b64 v[64:65], 10, v[64:65]
	v_cvt_pk_bf16_f32 v66, v68, s0
	v_lshl_add_u64 v[64:65], v[96:97], 0, v[64:65]
	global_store_short v[64:65], v66, off
	v_add_u32_e32 v64, 41, v100
	v_sub_u32_e32 v65, 22, v100
	v_cndmask_b32_e64 v64, v65, v64, s[2:3]
	v_ashrrev_i32_e32 v65, 31, v64
	v_lshlrev_b64 v[64:65], 10, v[64:65]
	v_cvt_pk_bf16_f32 v66, v69, s0
	v_lshl_add_u64 v[64:65], v[96:97], 0, v[64:65]
	global_store_short v[64:65], v66, off
	v_add_u32_e32 v64, 42, v100
	v_sub_u32_e32 v65, 21, v100
	v_cndmask_b32_e64 v64, v65, v64, s[2:3]
	v_ashrrev_i32_e32 v65, 31, v64
	v_lshlrev_b64 v[64:65], 10, v[64:65]
	v_cvt_pk_bf16_f32 v66, v70, s0
	v_lshl_add_u64 v[64:65], v[96:97], 0, v[64:65]
	global_store_short v[64:65], v66, off
	v_add_u32_e32 v64, 43, v100
	v_sub_u32_e32 v65, 20, v100
	v_cndmask_b32_e64 v64, v65, v64, s[2:3]
	v_ashrrev_i32_e32 v65, 31, v64
	v_lshlrev_b64 v[64:65], 10, v[64:65]
	v_cvt_pk_bf16_f32 v66, v71, s0
	v_lshl_add_u64 v[64:65], v[96:97], 0, v[64:65]
	global_store_short v[64:65], v66, off
	v_add_u32_e32 v64, 48, v100
	v_sub_u32_e32 v65, 15, v100
	v_cndmask_b32_e64 v64, v65, v64, s[2:3]
	v_ashrrev_i32_e32 v65, 31, v64
	v_lshlrev_b64 v[64:65], 10, v[64:65]
	v_cvt_pk_bf16_f32 v66, v72, s0
	v_lshl_add_u64 v[64:65], v[96:97], 0, v[64:65]
	global_store_short v[64:65], v66, off
	v_add_u32_e32 v64, 49, v100
	v_sub_u32_e32 v65, 14, v100
	v_cndmask_b32_e64 v64, v65, v64, s[2:3]
	v_ashrrev_i32_e32 v65, 31, v64
	v_lshlrev_b64 v[64:65], 10, v[64:65]
	v_cvt_pk_bf16_f32 v66, v73, s0
	v_lshl_add_u64 v[64:65], v[96:97], 0, v[64:65]
	global_store_short v[64:65], v66, off
	v_add_u32_e32 v64, 50, v100
	v_sub_u32_e32 v65, 13, v100
	v_cndmask_b32_e64 v64, v65, v64, s[2:3]
	v_ashrrev_i32_e32 v65, 31, v64
	v_lshlrev_b64 v[64:65], 10, v[64:65]
	v_cvt_pk_bf16_f32 v66, v74, s0
	v_lshl_add_u64 v[64:65], v[96:97], 0, v[64:65]
	global_store_short v[64:65], v66, off
	v_add_u32_e32 v64, 51, v100
	v_sub_u32_e32 v65, 12, v100
	v_cndmask_b32_e64 v64, v65, v64, s[2:3]
	v_ashrrev_i32_e32 v65, 31, v64
	v_lshlrev_b64 v[64:65], 10, v[64:65]
	v_cvt_pk_bf16_f32 v66, v75, s0
	v_lshl_add_u64 v[64:65], v[96:97], 0, v[64:65]
	global_store_short v[64:65], v66, off
	v_add_u32_e32 v64, 56, v100
	v_sub_u32_e32 v65, 7, v100
	v_cndmask_b32_e64 v64, v65, v64, s[2:3]
	v_ashrrev_i32_e32 v65, 31, v64
	v_lshlrev_b64 v[64:65], 10, v[64:65]
	v_cvt_pk_bf16_f32 v66, v76, s0
	v_lshl_add_u64 v[64:65], v[96:97], 0, v[64:65]
	global_store_short v[64:65], v66, off
	v_add_u32_e32 v64, 57, v100
	v_sub_u32_e32 v65, 6, v100
	v_cndmask_b32_e64 v64, v65, v64, s[2:3]
	v_ashrrev_i32_e32 v65, 31, v64
	v_lshlrev_b64 v[64:65], 10, v[64:65]
	v_cvt_pk_bf16_f32 v66, v77, s0
	v_lshl_add_u64 v[64:65], v[96:97], 0, v[64:65]
	global_store_short v[64:65], v66, off
	v_add_u32_e32 v64, 58, v100
	v_sub_u32_e32 v65, 5, v100
	v_cndmask_b32_e64 v64, v65, v64, s[2:3]
	v_ashrrev_i32_e32 v65, 31, v64
	v_lshlrev_b64 v[64:65], 10, v[64:65]
	v_cvt_pk_bf16_f32 v66, v78, s0
	v_lshl_add_u64 v[64:65], v[96:97], 0, v[64:65]
	global_store_short v[64:65], v66, off
	v_add_u32_e32 v64, 59, v100
	v_sub_u32_e32 v65, 4, v100
	v_cndmask_b32_e64 v64, v65, v64, s[2:3]
	v_ashrrev_i32_e32 v65, 31, v64
	v_lshlrev_b64 v[64:65], 10, v[64:65]
	v_cvt_pk_bf16_f32 v66, v79, s0
	v_lshl_add_u64 v[64:65], v[96:97], 0, v[64:65]
	global_store_short v[64:65], v66, off
	v_mov_b64_e32 v[144:145], v[168:169]
	v_mov_b64_e32 v[76:77], v[132:133]
	v_mov_b64_e32 v[72:73], v[128:129]
	v_mov_b64_e32 v[68:69], v[140:141]
	v_mov_b64_e32 v[64:65], v[136:137]
	v_mov_b64_e32 v[146:147], v[170:171]
	v_mov_b64_e32 v[78:79], v[134:135]
	v_mov_b64_e32 v[74:75], v[130:131]
	v_mov_b64_e32 v[70:71], v[142:143]
	v_mov_b64_e32 v[66:67], v[138:139]
	v_mov_b32_e32 v80, v205
	s_barrier
	s_cbranch_scc1 .LBB0_611

; #define MFMA32(a, b, c) __builtin_amdgcn_mfma_f32_32x32x16_bf16((a), (b), (c), 0, 0, 0)
; DI float bflo(unsigned w) { return __uint_as_float(w << 16); }
; DI float bfhi(unsigned w) { return __uint_as_float(w & 0xffff0000u); }
; DI void dn_scan_item(const Params& p, int seqbase, int T, int h, int dir, char* lds) {
;     ...
;     auto compute = [&](int n, int par, URegs& U) {
;         int lane = lane0; asm volatile("" : "+v"(lane));
;         const int r32 = lane & 31, hh = lane >> 5;
;         const char* buf = lds + par * SL_BUF;
;         f32x16 vn[2], o[2];
; #pragma unroll
;         for (int pt = 0; pt < 2; ++pt) {
;             const unsigned uu[8] = {U.un[pt][0].x, U.un[pt][0].y, U.un[pt][0].z, U.un[pt][0].w, U.un[pt][1].x, U.un[pt][1].y, U.un[pt][1].z, U.un[pt][1].w};
; #pragma unroll
;             for (int e = 0; e < 8; ++e) { vn[pt][2 * e] = bflo(uu[e]); vn[pt][2 * e + 1] = bfhi(uu[e]); }
; #pragma unroll
;             for (int i = 0; i < 16; ++i) o[pt][i] = 0.f;
;         }
;         const float gl = __expf(U.gl);
;         if (n + 2 < N) uload(n + 2, U);
; #pragma unroll
;         for (int ks = 0; ks < 8; ++ks) {
;             const bf16x8 sb = pack8(S[ks >> 1], ks & 1);
;             const int off = (ks * 16 + 4 * hh) * 2;
; #pragma unroll
;             for (int pt = 0; pt < 2; ++pt) {
;                 const char* wr = buf + SL_W + (pt * 32 + r32) * 264 + off;
;                 const char* qr = buf + SL_QG + (pt * 32 + r32) * 264 + off;
;                 vn[pt] = MFMA32(ld2x64(wr, wr + 16), sb, vn[pt]);
;                 o[pt] = MFMA32(ld2x64(qr, qr + 16), sb, o[pt]);
;             }
;         }
;         bf16x8 vb[4];
; #pragma unroll
;         for (int kp = 0; kp < 4; ++kp) vb[kp] = pack8(vn[kp >> 1], kp & 1);
; #pragma unroll
;         for (int d = 0; d < 4; ++d) S[d] = S[d] * gl;
.LBB0_609:
	v_ashrrev_i32_e32 v162, 5, v81
	v_and_b32_e32 v161, 31, v81
	v_lshl_add_u32 v163, v162, 3, 0
	v_mad_u32_u24 v165, v161, s88, v163
	v_lshlrev_b32_e32 v112, 16, v68
	v_and_b32_e32 v113, 0xffff0000, v68
	v_lshlrev_b32_e32 v114, 16, v69
	v_and_b32_e32 v115, 0xffff0000, v69
	v_lshlrev_b32_e32 v116, 16, v70
	v_and_b32_e32 v117, 0xffff0000, v70
	v_lshlrev_b32_e32 v118, 16, v71
	v_and_b32_e32 v119, 0xffff0000, v71
	ds_read2_b64 v[68:71], v165 offset1:2
	ds_read2_b64 v[168:171], v165 offset0:4 offset1:6
	v_lshlrev_b32_e32 v120, 16, v64
	v_and_b32_e32 v121, 0xffff0000, v64
	v_mul_f32_e32 v64, 0x3fb8aa3b, v80
	v_lshlrev_b32_e32 v96, 16, v76
	v_and_b32_e32 v97, 0xffff0000, v76
	v_lshlrev_b32_e32 v98, 16, v77
	v_and_b32_e32 v99, 0xffff0000, v77
	v_lshlrev_b32_e32 v100, 16, v78
	v_and_b32_e32 v101, 0xffff0000, v78
	v_lshlrev_b32_e32 v102, 16, v79
	v_and_b32_e32 v103, 0xffff0000, v79
	v_lshlrev_b32_e32 v104, 16, v72
	v_and_b32_e32 v105, 0xffff0000, v72
	v_lshlrev_b32_e32 v106, 16, v73
	v_and_b32_e32 v107, 0xffff0000, v73
	v_lshlrev_b32_e32 v108, 16, v74
	v_and_b32_e32 v109, 0xffff0000, v74
	v_lshlrev_b32_e32 v110, 16, v75
	v_and_b32_e32 v111, 0xffff0000, v75
	v_lshlrev_b32_e32 v122, 16, v65
	v_and_b32_e32 v123, 0xffff0000, v65
	v_lshlrev_b32_e32 v124, 16, v66
	v_and_b32_e32 v125, 0xffff0000, v66
	v_lshlrev_b32_e32 v126, 16, v67
	v_and_b32_e32 v127, 0xffff0000, v67
	v_exp_f32_e32 v160, v64
	v_cvt_pk_bf16_f32 v64, v48, v49
	v_cvt_pk_bf16_f32 v65, v50, v51
	v_cvt_pk_bf16_f32 v66, v52, v53
	v_cvt_pk_bf16_f32 v67, v54, v55
	v_add_u32_e32 v164, 0x4000, v165
	v_cvt_pk_bf16_f32 v172, v56, v57
	s_waitcnt lgkmcnt(1)
	v_mfma_f32_32x32x16_bf16 v[96:111], v[68:71], v[64:67], v[96:111]
	ds_read2_b64 v[68:71], v164 offset0:64 offset1:66
	v_cvt_pk_bf16_f32 v173, v58, v59
	v_cvt_pk_bf16_f32 v174, v60, v61
	v_cvt_pk_bf16_f32 v175, v62, v63
	v_add_u32_e32 v166, 0x2000, v165
	v_add_u32_e32 v167, 0x6000, v165
	v_pk_mul_f32 v[62:63], v[62:63], v[160:161] op_sel_hi:[1,0]
	s_waitcnt lgkmcnt(1)
	v_mfma_f32_32x32x16_bf16 v[96:111], v[168:171], v[172:175], v[96:111]
	ds_read2_b64 v[168:171], v164 offset0:68 offset1:70
	v_mul_f32_e64 v60, v60, v160
	v_mul_f32_e64 v61, v61, v160
	v_mul_f32_e64 v58, v58, v160
	v_mul_f32_e64 v59, v59, v160
	v_pk_mul_f32 v[56:57], v[56:57], v[160:161] op_sel_hi:[1,0]
	v_pk_mul_f32 v[54:55], v[54:55], v[160:161] op_sel_hi:[1,0]
	v_pk_mul_f32 v[52:53], v[52:53], v[160:161] op_sel_hi:[1,0]
	v_pk_mul_f32 v[50:51], v[50:51], v[160:161] op_sel_hi:[1,0]
	s_waitcnt lgkmcnt(1)
	v_mfma_f32_32x32x16_bf16 v[80:95], v[68:71], v[64:67], 0
	ds_read2_b64 v[68:71], v166 offset0:32 offset1:34
	v_mul_f32_e64 v48, v48, v160
	v_mul_f32_e64 v49, v49, v160
	s_and_b64 s[24:25], s[2:3], exec
	s_cselect_b32 s12, s22, s15
	s_add_i32 s12, s12, s27
	s_lshl_b64 s[24:25], s[12:13], 16
	s_add_u32 s24, s19, s24
	s_waitcnt lgkmcnt(1)
	v_mfma_f32_32x32x16_bf16 v[80:95], v[168:171], v[172:175], v[80:95]
	ds_read2_b64 v[168:171], v166 offset0:36 offset1:38
	s_addc_u32 s25, s20, s25
	v_lshlrev_b32_e32 v184, 1, v161
	s_cmp_gt_u32 s22, 28
	v_mov_b32_e32 v207, v206
	s_waitcnt lgkmcnt(1)
	v_mfma_f32_32x32x16_bf16 v[112:127], v[68:71], v[64:67], v[112:127]
	ds_read2_b64 v[68:71], v167 offset0:96 offset1:98
	s_waitcnt lgkmcnt(1)
	v_mfma_f32_32x32x16_bf16 v[112:127], v[168:171], v[172:175], v[112:127]
	ds_read2_b64 v[168:171], v167 offset0:100 offset1:102
	s_waitcnt lgkmcnt(1)
	v_mfma_f32_32x32x16_bf16 v[64:79], v[68:71], v[64:67], 0
	s_waitcnt lgkmcnt(0)
	v_mfma_f32_32x32x16_bf16 v[64:79], v[168:171], v[172:175], v[64:79]
	ds_read2_b64 v[172:175], v165 offset0:8 offset1:10
	v_cvt_pk_bf16_f32 v168, v32, v33
	v_cvt_pk_bf16_f32 v169, v34, v35
	v_cvt_pk_bf16_f32 v170, v36, v37
	v_cvt_pk_bf16_f32 v171, v38, v39
	v_pk_mul_f32 v[38:39], v[38:39], v[160:161] op_sel_hi:[1,0]
	v_pk_mul_f32 v[36:37], v[36:37], v[160:161] op_sel_hi:[1,0]
	s_waitcnt lgkmcnt(0)
	v_mfma_f32_32x32x16_bf16 v[96:111], v[172:175], v[168:171], v[96:111]
	ds_read2_b64 v[172:175], v164 offset0:72 offset1:74
	v_mul_f32_e64 v34, v34, v160
	v_mul_f32_e64 v35, v35, v160
	v_mul_f32_e64 v32, v32, v160
	v_mul_f32_e64 v33, v33, v160
	s_waitcnt lgkmcnt(0)
	v_mfma_f32_32x32x16_bf16 v[80:95], v[172:175], v[168:171], v[80:95]
	ds_read2_b64 v[172:175], v166 offset0:40 offset1:42
	s_waitcnt lgkmcnt(0)
	v_mfma_f32_32x32x16_bf16 v[112:127], v[172:175], v[168:171], v[112:127]
	ds_read2_b64 v[172:175], v167 offset0:104 offset1:106
	s_waitcnt lgkmcnt(0)
	v_mfma_f32_32x32x16_bf16 v[64:79], v[172:175], v[168:171], v[64:79]
	ds_read2_b64 v[172:175], v165 offset0:12 offset1:14
	v_cvt_pk_bf16_f32 v168, v40, v41
	v_cvt_pk_bf16_f32 v169, v42, v43
	v_cvt_pk_bf16_f32 v170, v44, v45
	v_cvt_pk_bf16_f32 v171, v46, v47
	v_pk_mul_f32 v[46:47], v[46:47], v[160:161] op_sel_hi:[1,0]
	v_pk_mul_f32 v[44:45], v[44:45], v[160:161] op_sel_hi:[1,0]
	s_waitcnt lgkmcnt(0)
	v_mfma_f32_32x32x16_bf16 v[96:111], v[172:175], v[168:171], v[96:111]
	ds_read2_b64 v[172:175], v164 offset0:76 offset1:78
	v_mul_f32_e64 v42, v42, v160
	v_mul_f32_e64 v43, v43, v160
	v_mul_f32_e64 v40, v40, v160
	v_mul_f32_e64 v41, v41, v160
	s_waitcnt lgkmcnt(0)
	v_mfma_f32_32x32x16_bf16 v[80:95], v[172:175], v[168:171], v[80:95]
	ds_read2_b64 v[172:175], v166 offset0:44 offset1:46
	s_waitcnt lgkmcnt(0)
	v_mfma_f32_32x32x16_bf16 v[112:127], v[172:175], v[168:171], v[112:127]
	ds_read2_b64 v[172:175], v167 offset0:108 offset1:110
	s_waitcnt lgkmcnt(0)
	v_mfma_f32_32x32x16_bf16 v[64:79], v[172:175], v[168:171], v[64:79]
	ds_read2_b64 v[172:175], v165 offset0:16 offset1:18
	v_cvt_pk_bf16_f32 v168, v16, v17
	v_cvt_pk_bf16_f32 v169, v18, v19
	v_cvt_pk_bf16_f32 v170, v20, v21
	v_cvt_pk_bf16_f32 v171, v22, v23
	v_pk_mul_f32 v[22:23], v[22:23], v[160:161] op_sel_hi:[1,0]
	v_pk_mul_f32 v[20:21], v[20:21], v[160:161] op_sel_hi:[1,0]
	s_waitcnt lgkmcnt(0)
; #define MFMA32(a, b, c) __builtin_amdgcn_mfma_f32_32x32x16_bf16((a), (b), (c), 0, 0, 0)
; DI void dn_scan_item(const Params& p, int seqbase, int T, int h, int dir, char* lds) {
;     ...
;         for (int ks = 0; ks < 8; ++ks) {
;             const bf16x8 sb = pack8(S[ks >> 1], ks & 1);
;             const int off = (ks * 16 + 4 * hh) * 2;
; #pragma unroll
;             for (int pt = 0; pt < 2; ++pt) {
;                 const char* wr = buf + SL_W + (pt * 32 + r32) * 264 + off;
;                 const char* qr = buf + SL_QG + (pt * 32 + r32) * 264 + off;
;                 vn[pt] = MFMA32(ld2x64(wr, wr + 16), sb, vn[pt]);
;                 o[pt] = MFMA32(ld2x64(qr, qr + 16), sb, o[pt]);
;             }
;         }
;         bf16x8 vb[4];
; #pragma unroll
;         for (int kp = 0; kp < 4; ++kp) vb[kp] = pack8(vn[kp >> 1], kp & 1);
; #pragma unroll
;         for (int d = 0; d < 4; ++d) S[d] = S[d] * gl;
; #pragma unroll
;         for (int kp = 0; kp < 4; ++kp) {
;             const int off = (kp * 16 + 4 * hh) * 2;
; #pragma unroll
;             for (int pt = 0; pt < 2; ++pt) { const char* ar = buf + SL_AT + (pt * 32 + r32) * 136 + off; o[pt] = MFMA32(ld2x64(ar, ar + 16), vb[kp], o[pt]); }
; #pragma unroll
;             for (int d = 0; d < 4; ++d) { const char* kr = buf + SL_KDT + (d * 32 + r32) * 136 + off; S[d] = MFMA32(ld2x64(kr, kr + 16), vb[kp], S[d]); }
;         }
	v_mfma_f32_32x32x16_bf16 v[96:111], v[172:175], v[168:171], v[96:111]
	ds_read2_b64 v[172:175], v164 offset0:80 offset1:82
	v_mul_f32_e64 v18, v18, v160
	v_mul_f32_e64 v19, v19, v160
	v_mul_f32_e64 v16, v16, v160
	v_mul_f32_e64 v17, v17, v160
	s_waitcnt lgkmcnt(0)
	v_mfma_f32_32x32x16_bf16 v[80:95], v[172:175], v[168:171], v[80:95]
	ds_read2_b64 v[172:175], v166 offset0:48 offset1:50
	s_waitcnt lgkmcnt(0)
	v_mfma_f32_32x32x16_bf16 v[112:127], v[172:175], v[168:171], v[112:127]
	ds_read2_b64 v[172:175], v167 offset0:112 offset1:114
	s_waitcnt lgkmcnt(0)
	v_mfma_f32_32x32x16_bf16 v[64:79], v[172:175], v[168:171], v[64:79]
	ds_read2_b64 v[172:175], v165 offset0:20 offset1:22
	v_cvt_pk_bf16_f32 v168, v24, v25
	v_cvt_pk_bf16_f32 v169, v26, v27
	v_cvt_pk_bf16_f32 v170, v28, v29
	v_cvt_pk_bf16_f32 v171, v30, v31
	v_pk_mul_f32 v[30:31], v[30:31], v[160:161] op_sel_hi:[1,0]
	v_pk_mul_f32 v[28:29], v[28:29], v[160:161] op_sel_hi:[1,0]
	s_waitcnt lgkmcnt(0)
	v_mfma_f32_32x32x16_bf16 v[96:111], v[172:175], v[168:171], v[96:111]
	ds_read2_b64 v[172:175], v164 offset0:84 offset1:86
	v_mul_f32_e64 v26, v26, v160
	v_mul_f32_e64 v27, v27, v160
	v_mul_f32_e64 v24, v24, v160
	v_mul_f32_e64 v25, v25, v160
	s_waitcnt lgkmcnt(0)
	v_mfma_f32_32x32x16_bf16 v[80:95], v[172:175], v[168:171], v[80:95]
	ds_read2_b64 v[172:175], v166 offset0:52 offset1:54
	s_waitcnt lgkmcnt(0)
	v_mfma_f32_32x32x16_bf16 v[112:127], v[172:175], v[168:171], v[112:127]
	ds_read2_b64 v[172:175], v167 offset0:116 offset1:118
	s_waitcnt lgkmcnt(0)
	v_mfma_f32_32x32x16_bf16 v[64:79], v[172:175], v[168:171], v[64:79]
	ds_read2_b64 v[172:175], v165 offset0:24 offset1:26
	v_cvt_pk_bf16_f32 v168, v0, v1
	v_cvt_pk_bf16_f32 v169, v2, v3
	v_cvt_pk_bf16_f32 v170, v4, v5
	v_cvt_pk_bf16_f32 v171, v6, v7
	v_pk_mul_f32 v[6:7], v[6:7], v[160:161] op_sel_hi:[1,0]
	v_pk_mul_f32 v[4:5], v[4:5], v[160:161] op_sel_hi:[1,0]
	s_waitcnt lgkmcnt(0)
	v_mfma_f32_32x32x16_bf16 v[96:111], v[172:175], v[168:171], v[96:111]
	ds_read2_b64 v[172:175], v164 offset0:88 offset1:90
	v_mul_f32_e64 v2, v2, v160
	v_mul_f32_e64 v3, v3, v160
	v_mul_f32_e64 v0, v0, v160
	v_mul_f32_e64 v1, v1, v160
	s_waitcnt lgkmcnt(0)
	v_mfma_f32_32x32x16_bf16 v[80:95], v[172:175], v[168:171], v[80:95]
	ds_read2_b64 v[172:175], v166 offset0:56 offset1:58
	s_waitcnt lgkmcnt(0)
	v_mfma_f32_32x32x16_bf16 v[112:127], v[172:175], v[168:171], v[112:127]
	ds_read2_b64 v[172:175], v167 offset0:120 offset1:122
	s_waitcnt lgkmcnt(0)
	v_mfma_f32_32x32x16_bf16 v[64:79], v[172:175], v[168:171], v[64:79]
	ds_read2_b64 v[172:175], v165 offset0:28 offset1:30
	v_cvt_pk_bf16_f32 v168, v8, v9
	v_cvt_pk_bf16_f32 v169, v10, v11
	v_cvt_pk_bf16_f32 v170, v12, v13
	v_cvt_pk_bf16_f32 v171, v14, v15
	v_pk_mul_f32 v[14:15], v[14:15], v[160:161] op_sel_hi:[1,0]
	v_pk_mul_f32 v[12:13], v[12:13], v[160:161] op_sel_hi:[1,0]
	s_waitcnt lgkmcnt(0)
	v_mfma_f32_32x32x16_bf16 v[96:111], v[172:175], v[168:171], v[96:111]
	ds_read2_b64 v[172:175], v164 offset0:92 offset1:94
	v_mul_f32_e64 v10, v10, v160
	v_mul_f32_e64 v11, v11, v160
	v_mul_f32_e64 v8, v8, v160
	v_mul_f32_e64 v9, v9, v160
	s_nop 6
	v_cvt_pk_bf16_f32 v104, v104, v105
	s_waitcnt lgkmcnt(0)
	v_mfma_f32_32x32x16_bf16 v[80:95], v[172:175], v[168:171], v[80:95]
	ds_read2_b64 v[172:175], v166 offset0:60 offset1:62
	ds_read2_b64 v[164:167], v167 offset0:124 offset1:126
	v_cvt_pk_bf16_f32 v105, v106, v107
	v_cvt_pk_bf16_f32 v106, v108, v109
	v_cvt_pk_bf16_f32 v107, v110, v111
	s_waitcnt lgkmcnt(1)
	v_mfma_f32_32x32x16_bf16 v[112:127], v[172:175], v[168:171], v[112:127]
	v_mov_b64_e32 v[174:175], v[150:151]
	v_mov_b64_e32 v[172:173], v[148:149]
	s_waitcnt lgkmcnt(0)
	v_mfma_f32_32x32x16_bf16 v[64:79], v[164:167], v[168:171], v[64:79]
	v_cvt_pk_bf16_f32 v167, v102, v103
	s_nop 6
	v_cvt_pk_bf16_f32 v102, v116, v117
	v_mad_u32_u24 v116, v161, s89, v163
	v_add_u32_e32 v117, 0xc800, v116
	ds_read2_b64 v[108:111], v117 offset1:2
	v_cvt_pk_bf16_f32 v164, v96, v97
	v_cvt_pk_bf16_f32 v165, v98, v99
	v_cvt_pk_bf16_f32 v166, v100, v101
	v_cvt_pk_bf16_f32 v103, v118, v119
	v_add_u32_e32 v118, 0xd800, v116
	s_waitcnt lgkmcnt(0)
	v_mfma_f32_32x32x16_bf16 v[80:95], v[108:111], v[164:167], v[80:95]
	ds_read2_b64 v[108:111], v118 offset0:32 offset1:34
	v_add_u32_e32 v119, 0x8000, v116
	v_cvt_pk_bf16_f32 v100, v112, v113
	v_cvt_pk_bf16_f32 v101, v114, v115
	v_cvt_pk_bf16_f32 v96, v120, v121
	v_add_u32_e32 v120, 0x9000, v116
	v_add_u32_e32 v121, 0xa000, v116
	s_waitcnt lgkmcnt(0)
	v_mfma_f32_32x32x16_bf16 v[64:79], v[108:111], v[164:167], v[64:79]
	ds_read2_b64 v[108:111], v119 offset0:128 offset1:130
	ds_read2_b64 v[112:115], v119 offset0:132 offset1:134
	v_add_u32_e32 v116, 0xb000, v116
	v_cvt_pk_bf16_f32 v97, v122, v123
	v_cvt_pk_bf16_f32 v98, v124, v125
	v_cvt_pk_bf16_f32 v99, v126, v127
	v_mov_b64_e32 v[170:171], v[146:147]
	v_mov_b64_e32 v[168:169], v[144:145]
	s_waitcnt lgkmcnt(1)
	v_mfma_f32_32x32x16_bf16 v[48:63], v[108:111], v[164:167], v[48:63]
	ds_read2_b64 v[108:111], v120 offset0:160 offset1:162
	s_waitcnt lgkmcnt(0)
	v_mfma_f32_32x32x16_bf16 v[32:47], v[108:111], v[164:167], v[32:47]
	ds_read2_b64 v[108:111], v121 offset0:192 offset1:194
	s_waitcnt lgkmcnt(0)
	v_mfma_f32_32x32x16_bf16 v[16:31], v[108:111], v[164:167], v[16:31]
	ds_read2_b64 v[108:111], v116 offset0:224 offset1:226
	s_waitcnt lgkmcnt(0)
	v_mfma_f32_32x32x16_bf16 v[0:15], v[108:111], v[164:167], v[0:15]
	ds_read2_b64 v[108:111], v117 offset0:4 offset1:6
	v_mov_b64_e32 v[166:167], v[158:159]
	v_mov_b64_e32 v[164:165], v[156:157]
	s_waitcnt lgkmcnt(0)
	v_mfma_f32_32x32x16_bf16 v[80:95], v[108:111], v[104:107], v[80:95]
	ds_read2_b64 v[108:111], v118 offset0:36 offset1:38
	s_waitcnt lgkmcnt(0)
; #define MFMA32(a, b, c) __builtin_amdgcn_mfma_f32_32x32x16_bf16((a), (b), (c), 0, 0, 0)
; DI bf16_t f2bf(float x) { return (bf16_t)(cvtpk(x, 0.f) & 0xffffu); }
; DI int crow(int r, int hi) { return (r & 3) + 8 * (r >> 2) + 4 * hi; }
; DI void dn_scan_item(const Params& p, int seqbase, int T, int h, int dir, char* lds) {
;     ...
;         for (int kp = 0; kp < 4; ++kp) {
;             const int off = (kp * 16 + 4 * hh) * 2;
; #pragma unroll
;             for (int pt = 0; pt < 2; ++pt) { const char* ar = buf + SL_AT + (pt * 32 + r32) * 136 + off; o[pt] = MFMA32(ld2x64(ar, ar + 16), vb[kp], o[pt]); }
; #pragma unroll
;             for (int d = 0; d < 4; ++d) { const char* kr = buf + SL_KDT + (d * 32 + r32) * 136 + off; S[d] = MFMA32(ld2x64(kr, kr + 16), vb[kp], S[d]); }
;         }
;         const int cn = dir ? N - 1 - n : n; const size_t mrow0 = (size_t)(gch0 + cn) * 64;
; #pragma unroll
;         for (int pt = 0; pt < 2; ++pt)
; #pragma unroll
;             for (int i = 0; i < 16; ++i) {
;                 const int pi = pt * 32 + crow(i, hh), tl = dir ? 63 - pi : pi;
;                 Oout[(mrow0 + tl) * 512 + h * 128 + slab * 32 + r32] = f2bf(o[pt][i]);
;             }
	v_mfma_f32_32x32x16_bf16 v[64:79], v[108:111], v[104:107], v[64:79]
	ds_read2_b64 v[108:111], v120 offset0:164 offset1:166
	s_waitcnt lgkmcnt(0)
	v_mfma_f32_32x32x16_bf16 v[32:47], v[108:111], v[104:107], v[32:47]
	ds_read2_b64 v[108:111], v121 offset0:196 offset1:198
	s_waitcnt lgkmcnt(0)
	v_mfma_f32_32x32x16_bf16 v[16:31], v[108:111], v[104:107], v[16:31]
	ds_read2_b64 v[108:111], v116 offset0:228 offset1:230
	v_mfma_f32_32x32x16_bf16 v[48:63], v[112:115], v[104:107], v[48:63]
	s_waitcnt lgkmcnt(0)
	v_mfma_f32_32x32x16_bf16 v[0:15], v[108:111], v[104:107], v[0:15]
	ds_read2_b64 v[104:107], v117 offset0:8 offset1:10
	s_waitcnt lgkmcnt(0)
	v_mfma_f32_32x32x16_bf16 v[80:95], v[104:107], v[100:103], v[80:95]
	ds_read2_b64 v[104:107], v118 offset0:40 offset1:42
	s_waitcnt lgkmcnt(0)
	v_mfma_f32_32x32x16_bf16 v[64:79], v[104:107], v[100:103], v[64:79]
	ds_read2_b64 v[104:107], v119 offset0:136 offset1:138
	s_waitcnt lgkmcnt(0)
	v_mfma_f32_32x32x16_bf16 v[48:63], v[104:107], v[100:103], v[48:63]
	ds_read2_b64 v[104:107], v120 offset0:168 offset1:170
	s_waitcnt lgkmcnt(0)
	v_mfma_f32_32x32x16_bf16 v[32:47], v[104:107], v[100:103], v[32:47]
	ds_read2_b64 v[104:107], v121 offset0:200 offset1:202
	s_waitcnt lgkmcnt(0)
	v_mfma_f32_32x32x16_bf16 v[16:31], v[104:107], v[100:103], v[16:31]
	ds_read2_b64 v[104:107], v116 offset0:232 offset1:234
	s_waitcnt lgkmcnt(0)
	v_mfma_f32_32x32x16_bf16 v[0:15], v[104:107], v[100:103], v[0:15]
	ds_read2_b64 v[100:103], v117 offset0:12 offset1:14
	s_waitcnt lgkmcnt(0)
	v_mfma_f32_32x32x16_bf16 v[80:95], v[100:103], v[96:99], v[80:95]
	ds_read2_b64 v[100:103], v118 offset0:44 offset1:46
	s_waitcnt lgkmcnt(0)
	v_mfma_f32_32x32x16_bf16 v[64:79], v[100:103], v[96:99], v[64:79]
	ds_read2_b64 v[100:103], v119 offset0:140 offset1:142
	s_nop 7
	v_cvt_pk_bf16_f32 v80, v80, s0
	v_cvt_pk_bf16_f32 v82, v82, s0
	s_nop 0
	v_cvt_pk_bf16_f32 v64, v64, s0
	s_waitcnt lgkmcnt(0)
	v_mfma_f32_32x32x16_bf16 v[48:63], v[100:103], v[96:99], v[48:63]
	ds_read2_b64 v[100:103], v120 offset0:172 offset1:174
	v_cvt_pk_bf16_f32 v66, v66, s0
	s_waitcnt lgkmcnt(0)
	v_mfma_f32_32x32x16_bf16 v[32:47], v[100:103], v[96:99], v[32:47]
	ds_read2_b64 v[100:103], v121 offset0:204 offset1:206
	s_waitcnt lgkmcnt(0)
	v_mfma_f32_32x32x16_bf16 v[16:31], v[100:103], v[96:99], v[16:31]
	ds_read2_b64 v[100:103], v116 offset0:236 offset1:238
	s_waitcnt lgkmcnt(0)
	v_mfma_f32_32x32x16_bf16 v[0:15], v[100:103], v[96:99], v[0:15]
	v_lshlrev_b32_e32 v100, 2, v162
	v_sub_u32_e32 v98, 63, v100
	v_cndmask_b32_e64 v98, v98, v100, s[2:3]
	v_ashrrev_i32_e32 v99, 31, v98
	v_lshl_add_u64 v[96:97], s[24:25], 0, v[184:185]
	v_lshlrev_b64 v[98:99], 10, v[98:99]
	v_lshl_add_u64 v[98:99], v[96:97], 0, v[98:99]
	s_waitcnt vmcnt(0)
	global_store_short v[98:99], v80, off
	v_or_b32_e32 v80, 1, v100
	v_sub_u32_e32 v98, 63, v80
	v_cndmask_b32_e64 v80, v98, v80, s[2:3]
	v_cvt_pk_bf16_f32 v98, v81, s0
	v_ashrrev_i32_e32 v81, 31, v80
	v_lshlrev_b64 v[80:81], 10, v[80:81]
	v_lshl_add_u64 v[80:81], v[96:97], 0, v[80:81]
	global_store_short v[80:81], v98, off
	v_or_b32_e32 v80, 2, v100
	v_sub_u32_e32 v81, 63, v80
	v_cndmask_b32_e64 v80, v81, v80, s[2:3]
	v_ashrrev_i32_e32 v81, 31, v80
	v_lshlrev_b64 v[80:81], 10, v[80:81]
	v_lshl_add_u64 v[80:81], v[96:97], 0, v[80:81]
	global_store_short v[80:81], v82, off
	v_or_b32_e32 v80, 3, v100
	v_sub_u32_e32 v81, 63, v80
	v_cndmask_b32_e64 v80, v81, v80, s[2:3]
	v_ashrrev_i32_e32 v81, 31, v80
	v_lshlrev_b64 v[80:81], 10, v[80:81]
	v_cvt_pk_bf16_f32 v82, v83, s0
	v_lshl_add_u64 v[80:81], v[96:97], 0, v[80:81]
	global_store_short v[80:81], v82, off
	v_add_u32_e32 v80, 8, v100
	v_sub_u32_e32 v81, 55, v100
	v_cndmask_b32_e64 v80, v81, v80, s[2:3]
	v_ashrrev_i32_e32 v81, 31, v80
	v_lshlrev_b64 v[80:81], 10, v[80:81]
	v_cvt_pk_bf16_f32 v82, v84, s0
	v_lshl_add_u64 v[80:81], v[96:97], 0, v[80:81]
	global_store_short v[80:81], v82, off
	v_add_u32_e32 v80, 9, v100
	v_sub_u32_e32 v81, 54, v100
	v_cndmask_b32_e64 v80, v81, v80, s[2:3]
	v_ashrrev_i32_e32 v81, 31, v80
	v_lshlrev_b64 v[80:81], 10, v[80:81]
	v_cvt_pk_bf16_f32 v82, v85, s0
	v_lshl_add_u64 v[80:81], v[96:97], 0, v[80:81]
	global_store_short v[80:81], v82, off
	v_add_u32_e32 v80, 10, v100
	v_sub_u32_e32 v81, 53, v100
	v_cndmask_b32_e64 v80, v81, v80, s[2:3]
	v_ashrrev_i32_e32 v81, 31, v80
	v_lshlrev_b64 v[80:81], 10, v[80:81]
	v_cvt_pk_bf16_f32 v82, v86, s0
	v_lshl_add_u64 v[80:81], v[96:97], 0, v[80:81]
	global_store_short v[80:81], v82, off
	v_add_u32_e32 v80, 11, v100
	v_sub_u32_e32 v81, 52, v100
	v_cndmask_b32_e64 v80, v81, v80, s[2:3]
	v_ashrrev_i32_e32 v81, 31, v80
	v_lshlrev_b64 v[80:81], 10, v[80:81]
	v_cvt_pk_bf16_f32 v82, v87, s0
	v_lshl_add_u64 v[80:81], v[96:97], 0, v[80:81]
	global_store_short v[80:81], v82, off
	v_add_u32_e32 v80, 16, v100
	v_sub_u32_e32 v81, 47, v100
	v_cndmask_b32_e64 v80, v81, v80, s[2:3]
	v_ashrrev_i32_e32 v81, 31, v80
	v_lshlrev_b64 v[80:81], 10, v[80:81]
	v_cvt_pk_bf16_f32 v82, v88, s0
	v_lshl_add_u64 v[80:81], v[96:97], 0, v[80:81]
	global_store_short v[80:81], v82, off
	v_add_u32_e32 v80, 17, v100
	v_sub_u32_e32 v81, 46, v100
	v_cndmask_b32_e64 v80, v81, v80, s[2:3]
	v_ashrrev_i32_e32 v81, 31, v80
	v_lshlrev_b64 v[80:81], 10, v[80:81]
	v_cvt_pk_bf16_f32 v82, v89, s0
	v_lshl_add_u64 v[80:81], v[96:97], 0, v[80:81]
	global_store_short v[80:81], v82, off
	v_add_u32_e32 v80, 18, v100
	v_sub_u32_e32 v81, 45, v100
	v_cndmask_b32_e64 v80, v81, v80, s[2:3]
	v_ashrrev_i32_e32 v81, 31, v80
	v_lshlrev_b64 v[80:81], 10, v[80:81]
	v_cvt_pk_bf16_f32 v82, v90, s0
	v_lshl_add_u64 v[80:81], v[96:97], 0, v[80:81]
	global_store_short v[80:81], v82, off
	v_add_u32_e32 v80, 19, v100
; DI bf16_t f2bf(float x) { return (bf16_t)(cvtpk(x, 0.f) & 0xffffu); }
; DI int crow(int r, int hi) { return (r & 3) + 8 * (r >> 2) + 4 * hi; }
; DI void dn_scan_item(const Params& p, int seqbase, int T, int h, int dir, char* lds) {
;     ...
;     auto uload = [&](int n, URegs& U) {
;         int lane = lane0; asm volatile("" : "+v"(lane));
;         const int cn = dir ? N - 1 - n : n; const size_t ci = (size_t)((gch0 + cn) * 4 + h) * 2 + dir;
;         const bf16_t* Uc = UcB + ci * 8192;
; #pragma unroll
;         for (int pt = 0; pt < 2; ++pt) { const u32x4* sp = (const u32x4*)(Uc + ((slab * 2 + pt) * 64 + lane) * 16); U.un[pt][0] = sp[0]; U.un[pt][1] = sp[1]; }
;         U.gl = GcB[ci * 64 + 63];
;     };
;     ...
;         const int cn = dir ? N - 1 - n : n; const size_t mrow0 = (size_t)(gch0 + cn) * 64;
; #pragma unroll
;         for (int pt = 0; pt < 2; ++pt)
; #pragma unroll
;             for (int i = 0; i < 16; ++i) {
;                 const int pi = pt * 32 + crow(i, hh), tl = dir ? 63 - pi : pi;
;                 Oout[(mrow0 + tl) * 512 + h * 128 + slab * 32 + r32] = f2bf(o[pt][i]);
;             }
	v_sub_u32_e32 v81, 44, v100
	v_cndmask_b32_e64 v80, v81, v80, s[2:3]
	v_ashrrev_i32_e32 v81, 31, v80
	v_lshlrev_b64 v[80:81], 10, v[80:81]
	v_cvt_pk_bf16_f32 v82, v91, s0
	v_lshl_add_u64 v[80:81], v[96:97], 0, v[80:81]
	global_store_short v[80:81], v82, off
	v_add_u32_e32 v80, 24, v100
	v_sub_u32_e32 v81, 39, v100
	v_cndmask_b32_e64 v80, v81, v80, s[2:3]
	v_ashrrev_i32_e32 v81, 31, v80
	v_lshlrev_b64 v[80:81], 10, v[80:81]
	v_cvt_pk_bf16_f32 v82, v92, s0
	v_lshl_add_u64 v[80:81], v[96:97], 0, v[80:81]
	global_store_short v[80:81], v82, off
	v_add_u32_e32 v80, 25, v100
	v_sub_u32_e32 v81, 38, v100
	v_cndmask_b32_e64 v80, v81, v80, s[2:3]
	v_ashrrev_i32_e32 v81, 31, v80
	v_lshlrev_b64 v[80:81], 10, v[80:81]
	v_cvt_pk_bf16_f32 v82, v93, s0
	v_lshl_add_u64 v[80:81], v[96:97], 0, v[80:81]
	global_store_short v[80:81], v82, off
	v_add_u32_e32 v80, 26, v100
	v_sub_u32_e32 v81, 37, v100
	v_cndmask_b32_e64 v80, v81, v80, s[2:3]
	v_ashrrev_i32_e32 v81, 31, v80
	v_lshlrev_b64 v[80:81], 10, v[80:81]
	v_cvt_pk_bf16_f32 v82, v94, s0
	v_lshl_add_u64 v[80:81], v[96:97], 0, v[80:81]
	global_store_short v[80:81], v82, off
	v_add_u32_e32 v80, 27, v100
	v_sub_u32_e32 v81, 36, v100
	v_cndmask_b32_e64 v80, v81, v80, s[2:3]
	v_ashrrev_i32_e32 v81, 31, v80
	v_lshlrev_b64 v[80:81], 10, v[80:81]
	v_cvt_pk_bf16_f32 v82, v95, s0
	v_lshl_add_u64 v[80:81], v[96:97], 0, v[80:81]
	global_store_short v[80:81], v82, off
	v_add_u32_e32 v80, 32, v100
	v_sub_u32_e32 v81, 31, v100
	v_cndmask_b32_e64 v80, v81, v80, s[2:3]
	v_ashrrev_i32_e32 v81, 31, v80
	v_lshlrev_b64 v[80:81], 10, v[80:81]
	v_lshl_add_u64 v[80:81], v[96:97], 0, v[80:81]
	global_store_short v[80:81], v64, off
	v_add_u32_e32 v64, 33, v100
	v_sub_u32_e32 v80, 30, v100
	v_cndmask_b32_e64 v64, v80, v64, s[2:3]
	v_cvt_pk_bf16_f32 v80, v65, s0
	v_ashrrev_i32_e32 v65, 31, v64
	v_lshlrev_b64 v[64:65], 10, v[64:65]
	v_lshl_add_u64 v[64:65], v[96:97], 0, v[64:65]
	global_store_short v[64:65], v80, off
	v_add_u32_e32 v64, 34, v100
	v_sub_u32_e32 v65, 29, v100
	v_cndmask_b32_e64 v64, v65, v64, s[2:3]
	v_ashrrev_i32_e32 v65, 31, v64
	v_lshlrev_b64 v[64:65], 10, v[64:65]
	v_lshl_add_u64 v[64:65], v[96:97], 0, v[64:65]
	global_store_short v[64:65], v66, off
	v_add_u32_e32 v64, 35, v100
	v_sub_u32_e32 v65, 28, v100
	v_cndmask_b32_e64 v64, v65, v64, s[2:3]
	v_ashrrev_i32_e32 v65, 31, v64
	v_lshlrev_b64 v[64:65], 10, v[64:65]
	v_cvt_pk_bf16_f32 v66, v67, s0
	v_lshl_add_u64 v[64:65], v[96:97], 0, v[64:65]
	global_store_short v[64:65], v66, off
	v_add_u32_e32 v64, 40, v100
	v_sub_u32_e32 v65, 23, v100
	v_cndmask_b32_e64 v64, v65, v64, s[2:3]
	v_ashrrev_i32_e32 v65, 31, v64
	v_lshlrev_b64 v[64:65], 10, v[64:65]
	v_cvt_pk_bf16_f32 v66, v68, s0
	v_lshl_add_u64 v[64:65], v[96:97], 0, v[64:65]
	global_store_short v[64:65], v66, off
	v_add_u32_e32 v64, 41, v100
	v_sub_u32_e32 v65, 22, v100
	v_cndmask_b32_e64 v64, v65, v64, s[2:3]
	v_ashrrev_i32_e32 v65, 31, v64
	v_lshlrev_b64 v[64:65], 10, v[64:65]
	v_cvt_pk_bf16_f32 v66, v69, s0
	v_lshl_add_u64 v[64:65], v[96:97], 0, v[64:65]
	global_store_short v[64:65], v66, off
	v_add_u32_e32 v64, 42, v100
	v_sub_u32_e32 v65, 21, v100
	v_cndmask_b32_e64 v64, v65, v64, s[2:3]
	v_ashrrev_i32_e32 v65, 31, v64
	v_lshlrev_b64 v[64:65], 10, v[64:65]
	v_cvt_pk_bf16_f32 v66, v70, s0
	v_lshl_add_u64 v[64:65], v[96:97], 0, v[64:65]
	global_store_short v[64:65], v66, off
	v_add_u32_e32 v64, 43, v100
	v_sub_u32_e32 v65, 20, v100
	v_cndmask_b32_e64 v64, v65, v64, s[2:3]
	v_ashrrev_i32_e32 v65, 31, v64
	v_lshlrev_b64 v[64:65], 10, v[64:65]
	v_cvt_pk_bf16_f32 v66, v71, s0
	v_lshl_add_u64 v[64:65], v[96:97], 0, v[64:65]
	global_store_short v[64:65], v66, off
	v_add_u32_e32 v64, 48, v100
	v_sub_u32_e32 v65, 15, v100
	v_cndmask_b32_e64 v64, v65, v64, s[2:3]
	v_ashrrev_i32_e32 v65, 31, v64
	v_lshlrev_b64 v[64:65], 10, v[64:65]
	v_cvt_pk_bf16_f32 v66, v72, s0
	v_lshl_add_u64 v[64:65], v[96:97], 0, v[64:65]
	global_store_short v[64:65], v66, off
	v_add_u32_e32 v64, 49, v100
	v_sub_u32_e32 v65, 14, v100
	v_cndmask_b32_e64 v64, v65, v64, s[2:3]
	v_ashrrev_i32_e32 v65, 31, v64
	v_lshlrev_b64 v[64:65], 10, v[64:65]
	v_cvt_pk_bf16_f32 v66, v73, s0
	v_lshl_add_u64 v[64:65], v[96:97], 0, v[64:65]
	global_store_short v[64:65], v66, off
	v_add_u32_e32 v64, 50, v100
	v_sub_u32_e32 v65, 13, v100
	v_cndmask_b32_e64 v64, v65, v64, s[2:3]
	v_ashrrev_i32_e32 v65, 31, v64
	v_lshlrev_b64 v[64:65], 10, v[64:65]
	v_cvt_pk_bf16_f32 v66, v74, s0
	v_lshl_add_u64 v[64:65], v[96:97], 0, v[64:65]
	global_store_short v[64:65], v66, off
	v_add_u32_e32 v64, 51, v100
	v_sub_u32_e32 v65, 12, v100
	v_cndmask_b32_e64 v64, v65, v64, s[2:3]
	v_ashrrev_i32_e32 v65, 31, v64
	v_lshlrev_b64 v[64:65], 10, v[64:65]
	v_cvt_pk_bf16_f32 v66, v75, s0
	v_lshl_add_u64 v[64:65], v[96:97], 0, v[64:65]
	global_store_short v[64:65], v66, off
	v_add_u32_e32 v64, 56, v100
	v_sub_u32_e32 v65, 7, v100
	v_cndmask_b32_e64 v64, v65, v64, s[2:3]
	v_ashrrev_i32_e32 v65, 31, v64
	v_lshlrev_b64 v[64:65], 10, v[64:65]
	v_cvt_pk_bf16_f32 v66, v76, s0
	v_lshl_add_u64 v[64:65], v[96:97], 0, v[64:65]
	global_store_short v[64:65], v66, off
	v_add_u32_e32 v64, 57, v100
	v_sub_u32_e32 v65, 6, v100
	v_cndmask_b32_e64 v64, v65, v64, s[2:3]
	v_ashrrev_i32_e32 v65, 31, v64
	v_lshlrev_b64 v[64:65], 10, v[64:65]
	v_cvt_pk_bf16_f32 v66, v77, s0
	v_lshl_add_u64 v[64:65], v[96:97], 0, v[64:65]
	global_store_short v[64:65], v66, off
	v_add_u32_e32 v64, 58, v100
	v_sub_u32_e32 v65, 5, v100
	v_cndmask_b32_e64 v64, v65, v64, s[2:3]
	v_ashrrev_i32_e32 v65, 31, v64
	v_lshlrev_b64 v[64:65], 10, v[64:65]
	v_cvt_pk_bf16_f32 v66, v78, s0
	v_lshl_add_u64 v[64:65], v[96:97], 0, v[64:65]
	global_store_short v[64:65], v66, off
	v_add_u32_e32 v64, 59, v100
	v_sub_u32_e32 v65, 4, v100
	v_cndmask_b32_e64 v64, v65, v64, s[2:3]
	v_ashrrev_i32_e32 v65, 31, v64
	v_lshlrev_b64 v[64:65], 10, v[64:65]
	v_cvt_pk_bf16_f32 v66, v79, s0
	v_lshl_add_u64 v[64:65], v[96:97], 0, v[64:65]
	v_mov_b64_e32 v[162:163], v[154:155]
	global_store_short v[64:65], v66, off
	v_mov_b32_e32 v64, v204
	v_mov_b64_e32 v[160:161], v[152:153]
	s_barrier
	s_cbranch_scc1 .LBB0_606
	s_add_i32 s12, s15, -3
	s_and_b64 s[24:25], s[2:3], exec
	s_cselect_b32 s12, s16, s12
	s_add_i32 s12, s12, s27
	v_mov_b32_e32 v65, v204
	s_lshl_b32 s12, s12, 3
	s_or_b32 s12, s12, s21
	s_lshl_b64 s[24:25], s[12:13], 14
	v_lshlrev_b32_e32 v65, 4, v65
	s_add_u32 s24, s76, s24
	v_add_u32_e32 v66, s17, v65
	s_addc_u32 s25, s77, s25
	v_ashrrev_i32_e32 v67, 31, v66
	v_lshl_add_u64 v[66:67], v[66:67], 1, s[24:25]
	global_load_dwordx4 v[160:163], v[66:67], off offset:16
	global_load_dwordx4 v[164:167], v[66:67], off
	v_add_u32_e32 v66, s18, v65
	v_ashrrev_i32_e32 v67, 31, v66
	v_lshl_add_u64 v[66:67], v[66:67], 1, s[24:25]
	s_lshl_b64 s[24:25], s[12:13], 8
	s_add_u32 s24, s78, s24
	s_addc_u32 s25, s79, s25
	global_load_dwordx4 v[168:171], v[66:67], off offset:16
	global_load_dwordx4 v[172:175], v[66:67], off
	global_load_dword v207, v185, s[24:25] offset:252
	s_branch .LBB0_606

; #define MFMA32(a, b, c) __builtin_amdgcn_mfma_f32_32x32x16_bf16((a), (b), (c), 0, 0, 0)
; DI float bflo(unsigned w) { return __uint_as_float(w << 16); }
; DI float bfhi(unsigned w) { return __uint_as_float(w & 0xffff0000u); }
; DI void dn_scan_item(const Params& p, int seqbase, int T, int h, int dir, char* lds) {
;     ...
;     auto compute = [&](int n, int par, URegs& U) {
;         int lane = lane0; asm volatile("" : "+v"(lane));
;         const int r32 = lane & 31, hh = lane >> 5;
;         const char* buf = lds + par * SL_BUF;
;         f32x16 vn[2], o[2];
; #pragma unroll
;         for (int pt = 0; pt < 2; ++pt) {
;             const unsigned uu[8] = {U.un[pt][0].x, U.un[pt][0].y, U.un[pt][0].z, U.un[pt][0].w, U.un[pt][1].x, U.un[pt][1].y, U.un[pt][1].z, U.un[pt][1].w};
; #pragma unroll
;             for (int e = 0; e < 8; ++e) { vn[pt][2 * e] = bflo(uu[e]); vn[pt][2 * e + 1] = bfhi(uu[e]); }
; #pragma unroll
;             for (int i = 0; i < 16; ++i) o[pt][i] = 0.f;
;         }
;         const float gl = __expf(U.gl);
;         if (n + 2 < N) uload(n + 2, U);
; #pragma unroll
;         for (int ks = 0; ks < 8; ++ks) {
;             const bf16x8 sb = pack8(S[ks >> 1], ks & 1);
;             const int off = (ks * 16 + 4 * hh) * 2;
; #pragma unroll
;             for (int pt = 0; pt < 2; ++pt) {
;                 const char* wr = buf + SL_W + (pt * 32 + r32) * 264 + off;
;                 const char* qr = buf + SL_QG + (pt * 32 + r32) * 264 + off;
;                 vn[pt] = MFMA32(ld2x64(wr, wr + 16), sb, vn[pt]);
;                 o[pt] = MFMA32(ld2x64(qr, qr + 16), sb, o[pt]);
;             }
;         }
.LBB0_624:
	v_lshlrev_b32_e32 v122, 16, v145
	v_and_b32_e32 v123, 0xffff0000, v145
	v_ashrrev_i32_e32 v145, 5, v64
	v_lshlrev_b32_e32 v124, 16, v146
	v_and_b32_e32 v125, 0xffff0000, v146
	v_lshlrev_b32_e32 v146, 3, v145
	v_and_b32_e32 v184, 31, v64
	v_add_u32_e32 v72, 0, v146
	v_mad_u32_u24 v68, v184, s88, v72
	v_lshlrev_b32_e32 v116, 16, v150
	v_and_b32_e32 v117, 0xffff0000, v150
	v_add_u32_e32 v150, 0xe800, v68
	v_lshlrev_b32_e32 v96, 16, v156
	v_and_b32_e32 v97, 0xffff0000, v156
	v_lshlrev_b32_e32 v98, 16, v157
	v_and_b32_e32 v99, 0xffff0000, v157
	v_lshlrev_b32_e32 v108, 16, v154
	v_and_b32_e32 v109, 0xffff0000, v154
	v_lshlrev_b32_e32 v110, 16, v155
	v_and_b32_e32 v111, 0xffff0000, v155
	ds_read2_b64 v[68:71], v150 offset0:64 offset1:66
	ds_read2_b64 v[154:157], v150 offset0:68 offset1:70
	v_mul_f32_e32 v64, 0x3fb8aa3b, v206
	v_add_u32_e32 v73, s90, v146
	v_lshlrev_b32_e32 v100, 16, v158
	v_and_b32_e32 v101, 0xffff0000, v158
	v_lshlrev_b32_e32 v102, 16, v159
	v_and_b32_e32 v103, 0xffff0000, v159
	v_lshlrev_b32_e32 v104, 16, v152
	v_and_b32_e32 v105, 0xffff0000, v152
	v_lshlrev_b32_e32 v106, 16, v153
	v_and_b32_e32 v107, 0xffff0000, v153
	v_lshlrev_b32_e32 v120, 16, v144
	v_and_b32_e32 v121, 0xffff0000, v144
	v_exp_f32_e32 v144, v64
	v_cvt_pk_bf16_f32 v64, v48, v49
	v_cvt_pk_bf16_f32 v65, v50, v51
	v_cvt_pk_bf16_f32 v66, v52, v53
	v_cvt_pk_bf16_f32 v67, v54, v55
	v_mad_u32_u24 v74, v184, s88, v73
	v_lshlrev_b32_e32 v126, 16, v147
	s_waitcnt lgkmcnt(1)
	v_mfma_f32_32x32x16_bf16 v[96:111], v[68:71], v[64:67], v[96:111]
	ds_read2_b64 v[68:71], v74 offset1:2
	v_and_b32_e32 v127, 0xffff0000, v147
	v_mad_u32_u24 v147, v184, s88, v179
	v_lshlrev_b32_e32 v118, 16, v151
	v_and_b32_e32 v119, 0xffff0000, v151
	v_lshlrev_b32_e32 v112, 16, v148
	v_and_b32_e32 v113, 0xffff0000, v148
	s_waitcnt lgkmcnt(0)
	v_mfma_f32_32x32x16_bf16 v[80:95], v[68:71], v[64:67], 0
	v_add_u32_e32 v68, v72, v147
	v_add_u32_e32 v151, 0xe800, v68
	ds_read2_b64 v[68:71], v151 offset0:64 offset1:66
	ds_read2_b64 v[208:211], v151 offset0:68 offset1:70
	v_mov_b32_e32 v148, s90
	v_lshlrev_b32_e32 v114, 16, v149
	v_and_b32_e32 v115, 0xffff0000, v149
	v_add_u32_e32 v149, 32, v146
	v_mad_u32_u24 v153, v184, s88, v148
	v_cvt_pk_bf16_f32 v212, v56, v57
	v_cvt_pk_bf16_f32 v213, v58, v59
	v_cvt_pk_bf16_f32 v214, v60, v61
	v_cvt_pk_bf16_f32 v215, v62, v63
	v_add_u32_e32 v148, v153, v149
	v_add_u32_e32 v72, v73, v147
	v_mfma_f32_32x32x16_bf16 v[96:111], v[154:157], v[212:215], v[96:111]
	ds_read2_b64 v[154:157], v148 offset1:2
	v_add_u32_e32 v152, s90, v147
	v_add_u32_e32 v147, v152, v149
	v_mul_f32_e64 v62, v144, v62
	v_mul_f32_e64 v63, v144, v63
	v_pk_mul_f32 v[60:61], v[144:145], v[60:61] op_sel_hi:[0,1]
	v_pk_mul_f32 v[58:59], v[144:145], v[58:59] op_sel_hi:[0,1]
	v_pk_mul_f32 v[56:57], v[144:145], v[56:57] op_sel_hi:[0,1]
	s_waitcnt lgkmcnt(2)
	v_mfma_f32_32x32x16_bf16 v[112:127], v[68:71], v[64:67], v[112:127]
	ds_read2_b64 v[68:71], v72 offset1:2
	v_mul_f32_e64 v54, v144, v54
	v_mul_f32_e64 v55, v144, v55
	v_mul_f32_e64 v52, v144, v52
	v_mul_f32_e64 v53, v144, v53
	v_pk_mul_f32 v[50:51], v[144:145], v[50:51] op_sel_hi:[0,1]
	v_pk_mul_f32 v[48:49], v[144:145], v[48:49] op_sel_hi:[0,1]
	s_xor_b32 s22, s20, -2
	s_add_i32 s21, s19, -2
	s_waitcnt lgkmcnt(1)
	v_mfma_f32_32x32x16_bf16 v[80:95], v[154:157], v[212:215], v[80:95]
	ds_read2_b64 v[154:157], v147 offset1:2
	v_add_u32_e32 v147, 64, v146
	v_add_u32_e32 v148, v153, v147
	s_add_i32 s26, s22, 0x100
	s_and_b64 s[22:23], s[2:3], exec
	s_cselect_b32 s21, s21, s26
	s_add_i32 s22, s21, s25
	s_waitcnt lgkmcnt(1)
	v_mfma_f32_32x32x16_bf16 v[64:79], v[68:71], v[64:67], 0
	s_ashr_i32 s23, s22, 31
	s_lshl_b64 s[22:23], s[22:23], 16
	s_add_u32 s22, s17, s22
	s_addc_u32 s23, s18, s23
	s_add_i32 s19, s19, 2
	s_add_i32 s14, s14, -2
	s_cmpk_gt_u32 s20, 0xfd
	v_mfma_f32_32x32x16_bf16 v[112:127], v[208:211], v[212:215], v[112:127]
	ds_read2_b64 v[208:211], v150 offset0:72 offset1:74
	s_waitcnt lgkmcnt(1)
	v_mfma_f32_32x32x16_bf16 v[64:79], v[154:157], v[212:215], v[64:79]
	v_cvt_pk_bf16_f32 v154, v32, v33
	v_cvt_pk_bf16_f32 v155, v34, v35
	v_cvt_pk_bf16_f32 v156, v36, v37
	v_cvt_pk_bf16_f32 v157, v38, v39
	v_mul_f32_e64 v38, v144, v38
	v_mul_f32_e64 v39, v144, v39
	v_pk_mul_f32 v[36:37], v[144:145], v[36:37] op_sel_hi:[0,1]
	v_pk_mul_f32 v[34:35], v[144:145], v[34:35] op_sel_hi:[0,1]
	s_waitcnt lgkmcnt(0)
	v_mfma_f32_32x32x16_bf16 v[96:111], v[208:211], v[154:157], v[96:111]
	ds_read2_b64 v[208:211], v148 offset1:2
	v_add_u32_e32 v148, v152, v147
	v_mul_f32_e64 v32, v144, v32
	v_mul_f32_e64 v33, v144, v33
	s_waitcnt lgkmcnt(0)
	v_mfma_f32_32x32x16_bf16 v[80:95], v[208:211], v[154:157], v[80:95]
	ds_read2_b64 v[208:211], v151 offset0:72 offset1:74
	s_waitcnt lgkmcnt(0)
	v_mfma_f32_32x32x16_bf16 v[112:127], v[208:211], v[154:157], v[112:127]
	ds_read2_b64 v[208:211], v148 offset1:2
	v_add_u32_e32 v148, 0x60, v146
	v_add_u32_e32 v158, v153, v148
	s_waitcnt lgkmcnt(0)
	v_mfma_f32_32x32x16_bf16 v[64:79], v[208:211], v[154:157], v[64:79]
	ds_read2_b64 v[208:211], v150 offset0:76 offset1:78
	v_cvt_pk_bf16_f32 v154, v40, v41
	v_cvt_pk_bf16_f32 v155, v42, v43
	v_cvt_pk_bf16_f32 v156, v44, v45
	v_cvt_pk_bf16_f32 v157, v46, v47
	v_pk_mul_f32 v[46:47], v[144:145], v[46:47] op_sel_hi:[0,1]
	v_pk_mul_f32 v[44:45], v[144:145], v[44:45] op_sel_hi:[0,1]
	s_waitcnt lgkmcnt(0)
	v_mfma_f32_32x32x16_bf16 v[96:111], v[208:211], v[154:157], v[96:111]
	ds_read2_b64 v[208:211], v158 offset1:2
	v_add_u32_e32 v158, v152, v148
	v_mul_f32_e64 v42, v144, v42
	v_mul_f32_e64 v43, v144, v43
	v_mul_f32_e64 v40, v144, v40
	v_mul_f32_e64 v41, v144, v41
	s_waitcnt lgkmcnt(0)
; #define MFMA32(a, b, c) __builtin_amdgcn_mfma_f32_32x32x16_bf16((a), (b), (c), 0, 0, 0)
; DI void dn_scan_item(const Params& p, int seqbase, int T, int h, int dir, char* lds) {
;     ...
; #pragma unroll
;         for (int ks = 0; ks < 8; ++ks) {
;             const bf16x8 sb = pack8(S[ks >> 1], ks & 1);
;             const int off = (ks * 16 + 4 * hh) * 2;
; #pragma unroll
;             for (int pt = 0; pt < 2; ++pt) {
;                 const char* wr = buf + SL_W + (pt * 32 + r32) * 264 + off;
;                 const char* qr = buf + SL_QG + (pt * 32 + r32) * 264 + off;
;                 vn[pt] = MFMA32(ld2x64(wr, wr + 16), sb, vn[pt]);
;                 o[pt] = MFMA32(ld2x64(qr, qr + 16), sb, o[pt]);
;             }
;         }
;         bf16x8 vb[4];
; #pragma unroll
;         for (int kp = 0; kp < 4; ++kp) vb[kp] = pack8(vn[kp >> 1], kp & 1);
; #pragma unroll
;         for (int d = 0; d < 4; ++d) S[d] = S[d] * gl;
; #pragma unroll
;         for (int kp = 0; kp < 4; ++kp) {
;             const int off = (kp * 16 + 4 * hh) * 2;
; #pragma unroll
;             for (int pt = 0; pt < 2; ++pt) { const char* ar = buf + SL_AT + (pt * 32 + r32) * 136 + off; o[pt] = MFMA32(ld2x64(ar, ar + 16), vb[kp], o[pt]); }
; #pragma unroll
;             for (int d = 0; d < 4; ++d) { const char* kr = buf + SL_KDT + (d * 32 + r32) * 136 + off; S[d] = MFMA32(ld2x64(kr, kr + 16), vb[kp], S[d]); }
	v_mfma_f32_32x32x16_bf16 v[80:95], v[208:211], v[154:157], v[80:95]
	ds_read2_b64 v[208:211], v151 offset0:76 offset1:78
	s_waitcnt lgkmcnt(0)
	v_mfma_f32_32x32x16_bf16 v[112:127], v[208:211], v[154:157], v[112:127]
	ds_read2_b64 v[208:211], v158 offset1:2
	v_add_u32_e32 v158, 0x80, v146
	v_add_u32_e32 v159, v153, v158
	v_add_u32_e32 v158, v152, v158
	s_waitcnt lgkmcnt(0)
	v_mfma_f32_32x32x16_bf16 v[64:79], v[208:211], v[154:157], v[64:79]
	ds_read2_b64 v[208:211], v150 offset0:80 offset1:82
	v_cvt_pk_bf16_f32 v154, v16, v17
	v_cvt_pk_bf16_f32 v155, v18, v19
	v_cvt_pk_bf16_f32 v156, v20, v21
	v_cvt_pk_bf16_f32 v157, v22, v23
	v_pk_mul_f32 v[22:23], v[144:145], v[22:23] op_sel_hi:[0,1]
	v_pk_mul_f32 v[20:21], v[144:145], v[20:21] op_sel_hi:[0,1]
	s_waitcnt lgkmcnt(0)
	v_mfma_f32_32x32x16_bf16 v[96:111], v[208:211], v[154:157], v[96:111]
	ds_read2_b64 v[208:211], v159 offset1:2
	v_mul_f32_e64 v18, v144, v18
	v_mul_f32_e64 v19, v144, v19
	v_mul_f32_e64 v16, v144, v16
	v_mul_f32_e64 v17, v144, v17
	s_waitcnt lgkmcnt(0)
	v_mfma_f32_32x32x16_bf16 v[80:95], v[208:211], v[154:157], v[80:95]
	ds_read2_b64 v[208:211], v151 offset0:80 offset1:82
	s_waitcnt lgkmcnt(0)
	v_mfma_f32_32x32x16_bf16 v[112:127], v[208:211], v[154:157], v[112:127]
	ds_read2_b64 v[208:211], v158 offset1:2
	v_add_u32_e32 v158, 0xa0, v146
	v_add_u32_e32 v159, v153, v158
	v_add_u32_e32 v158, v152, v158
	s_waitcnt lgkmcnt(0)
	v_mfma_f32_32x32x16_bf16 v[64:79], v[208:211], v[154:157], v[64:79]
	ds_read2_b64 v[208:211], v150 offset0:84 offset1:86
	v_cvt_pk_bf16_f32 v154, v24, v25
	v_cvt_pk_bf16_f32 v155, v26, v27
	v_cvt_pk_bf16_f32 v156, v28, v29
	v_cvt_pk_bf16_f32 v157, v30, v31
	v_pk_mul_f32 v[30:31], v[144:145], v[30:31] op_sel_hi:[0,1]
	v_pk_mul_f32 v[28:29], v[144:145], v[28:29] op_sel_hi:[0,1]
	s_waitcnt lgkmcnt(0)
	v_mfma_f32_32x32x16_bf16 v[96:111], v[208:211], v[154:157], v[96:111]
	ds_read2_b64 v[208:211], v159 offset1:2
	v_mul_f32_e64 v26, v144, v26
	v_mul_f32_e64 v27, v144, v27
	v_mul_f32_e64 v24, v144, v24
	v_mul_f32_e64 v25, v144, v25
	s_waitcnt lgkmcnt(0)
	v_mfma_f32_32x32x16_bf16 v[80:95], v[208:211], v[154:157], v[80:95]
	ds_read2_b64 v[208:211], v151 offset0:84 offset1:86
	s_waitcnt lgkmcnt(0)
	v_mfma_f32_32x32x16_bf16 v[112:127], v[208:211], v[154:157], v[112:127]
	ds_read2_b64 v[208:211], v158 offset1:2
	v_add_u32_e32 v158, 0xc0, v146
	v_add_u32_e32 v159, v153, v158
	v_add_u32_e32 v158, v152, v158
	s_waitcnt lgkmcnt(0)
	v_mfma_f32_32x32x16_bf16 v[64:79], v[208:211], v[154:157], v[64:79]
	ds_read2_b64 v[208:211], v150 offset0:88 offset1:90
	v_cvt_pk_bf16_f32 v154, v0, v1
	v_cvt_pk_bf16_f32 v155, v2, v3
	v_cvt_pk_bf16_f32 v156, v4, v5
	v_cvt_pk_bf16_f32 v157, v6, v7
	v_pk_mul_f32 v[6:7], v[144:145], v[6:7] op_sel_hi:[0,1]
	v_pk_mul_f32 v[4:5], v[144:145], v[4:5] op_sel_hi:[0,1]
	s_waitcnt lgkmcnt(0)
	v_mfma_f32_32x32x16_bf16 v[96:111], v[208:211], v[154:157], v[96:111]
	ds_read2_b64 v[208:211], v159 offset1:2
	v_mul_f32_e64 v2, v144, v2
	v_mul_f32_e64 v3, v144, v3
	v_mul_f32_e64 v0, v144, v0
	v_mul_f32_e64 v1, v144, v1
	s_waitcnt lgkmcnt(0)
	v_mfma_f32_32x32x16_bf16 v[80:95], v[208:211], v[154:157], v[80:95]
	ds_read2_b64 v[208:211], v151 offset0:88 offset1:90
	s_waitcnt lgkmcnt(0)
	v_mfma_f32_32x32x16_bf16 v[112:127], v[208:211], v[154:157], v[112:127]
	ds_read2_b64 v[208:211], v158 offset1:2
	v_add_u32_e32 v158, 0xe0, v146
	v_add_u32_e32 v153, v153, v158
	v_add_u32_e32 v158, v152, v158
	s_waitcnt lgkmcnt(0)
	v_mfma_f32_32x32x16_bf16 v[64:79], v[208:211], v[154:157], v[64:79]
	ds_read2_b64 v[208:211], v150 offset0:92 offset1:94
	v_cvt_pk_bf16_f32 v154, v8, v9
	v_cvt_pk_bf16_f32 v155, v10, v11
	v_cvt_pk_bf16_f32 v156, v12, v13
	v_cvt_pk_bf16_f32 v157, v14, v15
	v_pk_mul_f32 v[14:15], v[144:145], v[14:15] op_sel_hi:[0,1]
	v_pk_mul_f32 v[12:13], v[144:145], v[12:13] op_sel_hi:[0,1]
	s_waitcnt lgkmcnt(0)
	v_mfma_f32_32x32x16_bf16 v[96:111], v[208:211], v[154:157], v[96:111]
	ds_read2_b64 v[208:211], v153 offset1:2
	ds_read2_b64 v[150:153], v151 offset0:92 offset1:94
	v_mul_f32_e64 v10, v144, v10
	v_mul_f32_e64 v11, v144, v11
	v_mul_f32_e64 v8, v144, v8
	v_mul_f32_e64 v9, v144, v9
	s_nop 5
	v_cvt_pk_bf16_f32 v104, v104, v105
	s_waitcnt lgkmcnt(0)
	v_mfma_f32_32x32x16_bf16 v[112:127], v[150:153], v[154:157], v[112:127]
	ds_read2_b64 v[150:153], v158 offset1:2
	v_cvt_pk_bf16_f32 v105, v106, v107
	v_cvt_pk_bf16_f32 v106, v108, v109
	v_cvt_pk_bf16_f32 v107, v110, v111
	s_waitcnt lgkmcnt(0)
	v_mfma_f32_32x32x16_bf16 v[64:79], v[150:153], v[154:157], v[64:79]
	v_cvt_pk_bf16_f32 v152, v100, v101
	s_nop 4
	v_cvt_pk_bf16_f32 v100, v112, v113
	v_add_u32_e32 v113, s91, v146
	v_mad_u32_u24 v108, v184, s89, v113
	ds_read2_b64 v[108:111], v108 offset1:2
	v_cvt_pk_bf16_f32 v150, v96, v97
	v_cvt_pk_bf16_f32 v151, v98, v99
	v_mfma_f32_32x32x16_bf16 v[80:95], v[208:211], v[154:157], v[80:95]
	v_cvt_pk_bf16_f32 v153, v102, v103
	v_cvt_pk_bf16_f32 v101, v114, v115
	v_mad_u32_u24 v114, v184, s89, v181
	v_cvt_pk_bf16_f32 v102, v116, v117
	v_mul_u32_u24_e32 v112, 0x88, v184
	v_add3_u32 v117, s92, v149, v112
	v_cvt_pk_bf16_f32 v103, v118, v119
	s_waitcnt lgkmcnt(0)
	v_mfma_f32_32x32x16_bf16 v[80:95], v[108:111], v[150:153], v[80:95]
	v_add_u32_e32 v108, v113, v114
	ds_read2_b64 v[108:111], v108 offset1:2
	v_add_u32_e32 v113, s92, v146
	v_mad_u32_u24 v115, v184, s89, v113
	v_cvt_pk_bf16_f32 v96, v120, v121
	v_cvt_pk_bf16_f32 v97, v122, v123
	v_cvt_pk_bf16_f32 v98, v124, v125
	s_waitcnt lgkmcnt(0)
	v_mfma_f32_32x32x16_bf16 v[64:79], v[108:111], v[150:153], v[64:79]
	ds_read2_b64 v[108:111], v115 offset1:2
	v_cvt_pk_bf16_f32 v99, v126, v127
	s_waitcnt vmcnt(0)
; #define MFMA32(a, b, c) __builtin_amdgcn_mfma_f32_32x32x16_bf16((a), (b), (c), 0, 0, 0)
; DI void dn_scan_item(const Params& p, int seqbase, int T, int h, int dir, char* lds) {
;     ...
;         bf16x8 vb[4];
; #pragma unroll
;         for (int kp = 0; kp < 4; ++kp) vb[kp] = pack8(vn[kp >> 1], kp & 1);
; #pragma unroll
;         for (int d = 0; d < 4; ++d) S[d] = S[d] * gl;
; #pragma unroll
;         for (int kp = 0; kp < 4; ++kp) {
;             const int off = (kp * 16 + 4 * hh) * 2;
; #pragma unroll
;             for (int pt = 0; pt < 2; ++pt) { const char* ar = buf + SL_AT + (pt * 32 + r32) * 136 + off; o[pt] = MFMA32(ld2x64(ar, ar + 16), vb[kp], o[pt]); }
; #pragma unroll
;             for (int d = 0; d < 4; ++d) { const char* kr = buf + SL_KDT + (d * 32 + r32) * 136 + off; S[d] = MFMA32(ld2x64(kr, kr + 16), vb[kp], S[d]); }
;         }
	v_mov_b32_e32 v206, v207
	v_mov_b64_e32 v[156:157], v[164:165]
	v_mov_b64_e32 v[158:159], v[166:167]
	s_waitcnt lgkmcnt(0)
	v_mfma_f32_32x32x16_bf16 v[48:63], v[108:111], v[150:153], v[48:63]
	v_add_u32_e32 v108, v113, v114
	ds_read2_b64 v[108:111], v108 offset1:2
	s_waitcnt lgkmcnt(0)
	v_mfma_f32_32x32x16_bf16 v[32:47], v[108:111], v[150:153], v[32:47]
	v_add_u32_e32 v108, 0x2000, v115
	ds_read2_b64 v[108:111], v108 offset0:64 offset1:66
	s_waitcnt lgkmcnt(0)
	v_mfma_f32_32x32x16_bf16 v[16:31], v[108:111], v[150:153], v[16:31]
	v_add_u32_e32 v108, 0x3000, v115
	ds_read2_b64 v[108:111], v108 offset0:96 offset1:98
	v_add_u32_e32 v115, s91, v114
	v_add_u32_e32 v114, s92, v114
	s_waitcnt lgkmcnt(0)
	v_mfma_f32_32x32x16_bf16 v[0:15], v[108:111], v[150:153], v[0:15]
	v_mov_b32_e32 v108, s91
	v_mad_u32_u24 v113, v184, s89, v108
	v_add_u32_e32 v108, v113, v149
	ds_read2_b64 v[108:111], v108 offset1:2
	v_mov_b64_e32 v[152:153], v[160:161]
	v_mov_b64_e32 v[154:155], v[162:163]
	s_waitcnt lgkmcnt(0)
	v_mfma_f32_32x32x16_bf16 v[80:95], v[108:111], v[104:107], v[80:95]
	v_add_u32_e32 v108, v115, v149
	ds_read2_b64 v[108:111], v108 offset1:2
	s_waitcnt lgkmcnt(0)
	v_mfma_f32_32x32x16_bf16 v[64:79], v[108:111], v[104:107], v[64:79]
	v_mov_b32_e32 v108, s92
	v_mad_u32_u24 v116, v184, s89, v108
	v_add_u32_e32 v108, v116, v149
	ds_read2_b64 v[108:111], v108 offset1:2
	v_lshlrev_b32_e32 v184, 1, v184
	s_waitcnt lgkmcnt(0)
	v_mfma_f32_32x32x16_bf16 v[48:63], v[108:111], v[104:107], v[48:63]
	v_add_u32_e32 v108, v114, v149
	ds_read2_b64 v[108:111], v108 offset1:2
	s_waitcnt lgkmcnt(0)
	v_mfma_f32_32x32x16_bf16 v[32:47], v[108:111], v[104:107], v[32:47]
	v_add_u32_e32 v108, 0x2000, v117
	ds_read2_b64 v[108:111], v108 offset0:64 offset1:66
	s_waitcnt lgkmcnt(0)
	v_mfma_f32_32x32x16_bf16 v[16:31], v[108:111], v[104:107], v[16:31]
	v_add_u32_e32 v108, 0x3000, v117
	ds_read2_b64 v[108:111], v108 offset0:96 offset1:98
	s_waitcnt lgkmcnt(0)
	v_mfma_f32_32x32x16_bf16 v[0:15], v[108:111], v[104:107], v[0:15]
	v_add_u32_e32 v104, v113, v147
	ds_read2_b64 v[104:107], v104 offset1:2
	v_add3_u32 v108, s92, v147, v112
	s_waitcnt lgkmcnt(0)
	v_mfma_f32_32x32x16_bf16 v[80:95], v[104:107], v[100:103], v[80:95]
	v_add_u32_e32 v104, v115, v147
	ds_read2_b64 v[104:107], v104 offset1:2
	s_waitcnt lgkmcnt(0)
	v_mfma_f32_32x32x16_bf16 v[64:79], v[104:107], v[100:103], v[64:79]
	v_add_u32_e32 v104, v116, v147
	ds_read2_b64 v[104:107], v104 offset1:2
	s_waitcnt lgkmcnt(0)
	v_mfma_f32_32x32x16_bf16 v[48:63], v[104:107], v[100:103], v[48:63]
	v_add_u32_e32 v104, v114, v147
	ds_read2_b64 v[104:107], v104 offset1:2
	s_waitcnt lgkmcnt(0)
	v_mfma_f32_32x32x16_bf16 v[32:47], v[104:107], v[100:103], v[32:47]
	v_add_u32_e32 v104, 0x2000, v108
	ds_read2_b64 v[104:107], v104 offset0:64 offset1:66
	s_waitcnt lgkmcnt(0)
	v_mfma_f32_32x32x16_bf16 v[16:31], v[104:107], v[100:103], v[16:31]
	v_add_u32_e32 v104, 0x3000, v108
	ds_read2_b64 v[104:107], v104 offset0:96 offset1:98
	s_waitcnt lgkmcnt(0)
	v_mfma_f32_32x32x16_bf16 v[0:15], v[104:107], v[100:103], v[0:15]
	v_add_u32_e32 v100, v113, v148
	ds_read2_b64 v[100:103], v100 offset1:2
	v_add3_u32 v104, s92, v148, v112
	s_waitcnt lgkmcnt(0)
	v_mfma_f32_32x32x16_bf16 v[80:95], v[100:103], v[96:99], v[80:95]
	v_add_u32_e32 v100, v115, v148
	ds_read2_b64 v[100:103], v100 offset1:2
	s_nop 9
	v_cvt_pk_bf16_f32 v80, v80, s0
	s_waitcnt lgkmcnt(0)
	v_mfma_f32_32x32x16_bf16 v[64:79], v[100:103], v[96:99], v[64:79]
	v_add_u32_e32 v100, v116, v148
	ds_read2_b64 v[100:103], v100 offset1:2
	v_cvt_pk_bf16_f32 v82, v82, s0
	s_nop 8
	v_cvt_pk_bf16_f32 v64, v64, s0
	s_waitcnt lgkmcnt(0)
	v_mfma_f32_32x32x16_bf16 v[48:63], v[100:103], v[96:99], v[48:63]
	v_add_u32_e32 v100, v114, v148
	ds_read2_b64 v[100:103], v100 offset1:2
	v_cvt_pk_bf16_f32 v66, v66, s0
	v_mov_b64_e32 v[148:149], v[172:173]
	v_mov_b64_e32 v[150:151], v[174:175]
	s_waitcnt lgkmcnt(0)
	v_mfma_f32_32x32x16_bf16 v[32:47], v[100:103], v[96:99], v[32:47]
	v_add_u32_e32 v100, 0x2000, v104
	ds_read2_b64 v[100:103], v100 offset0:64 offset1:66
	s_waitcnt lgkmcnt(0)
	v_mfma_f32_32x32x16_bf16 v[16:31], v[100:103], v[96:99], v[16:31]
	v_add_u32_e32 v100, 0x3000, v104
	ds_read2_b64 v[100:103], v100 offset0:96 offset1:98
	s_waitcnt lgkmcnt(0)
; #define MFMA32(a, b, c) __builtin_amdgcn_mfma_f32_32x32x16_bf16((a), (b), (c), 0, 0, 0)
; DI bf16_t f2bf(float x) { return (bf16_t)(cvtpk(x, 0.f) & 0xffffu); }
; DI int crow(int r, int hi) { return (r & 3) + 8 * (r >> 2) + 4 * hi; }
; DI void dn_scan_item(const Params& p, int seqbase, int T, int h, int dir, char* lds) {
;     ...
;         for (int kp = 0; kp < 4; ++kp) {
;             const int off = (kp * 16 + 4 * hh) * 2;
; #pragma unroll
;             for (int pt = 0; pt < 2; ++pt) { const char* ar = buf + SL_AT + (pt * 32 + r32) * 136 + off; o[pt] = MFMA32(ld2x64(ar, ar + 16), vb[kp], o[pt]); }
; #pragma unroll
;             for (int d = 0; d < 4; ++d) { const char* kr = buf + SL_KDT + (d * 32 + r32) * 136 + off; S[d] = MFMA32(ld2x64(kr, kr + 16), vb[kp], S[d]); }
;         }
;         const int cn = dir ? N - 1 - n : n; const size_t mrow0 = (size_t)(gch0 + cn) * 64;
; #pragma unroll
;         for (int pt = 0; pt < 2; ++pt)
; #pragma unroll
;             for (int i = 0; i < 16; ++i) {
;                 const int pi = pt * 32 + crow(i, hh), tl = dir ? 63 - pi : pi;
;                 Oout[(mrow0 + tl) * 512 + h * 128 + slab * 32 + r32] = f2bf(o[pt][i]);
;             }
	v_mfma_f32_32x32x16_bf16 v[0:15], v[100:103], v[96:99], v[0:15]
	v_lshlrev_b32_e32 v100, 2, v145
	v_sub_u32_e32 v98, 63, v100
	v_cndmask_b32_e64 v98, v98, v100, s[2:3]
	v_ashrrev_i32_e32 v99, 31, v98
	v_lshl_add_u64 v[96:97], s[22:23], 0, v[184:185]
	v_lshlrev_b64 v[98:99], 10, v[98:99]
	v_lshl_add_u64 v[98:99], v[96:97], 0, v[98:99]
	global_store_short v[98:99], v80, off
	v_or_b32_e32 v80, 1, v100
	v_sub_u32_e32 v98, 63, v80
	v_cndmask_b32_e64 v80, v98, v80, s[2:3]
	v_cvt_pk_bf16_f32 v98, v81, s0
	v_ashrrev_i32_e32 v81, 31, v80
	v_lshlrev_b64 v[80:81], 10, v[80:81]
	v_lshl_add_u64 v[80:81], v[96:97], 0, v[80:81]
	global_store_short v[80:81], v98, off
	v_or_b32_e32 v80, 2, v100
	v_sub_u32_e32 v81, 63, v80
	v_cndmask_b32_e64 v80, v81, v80, s[2:3]
	v_ashrrev_i32_e32 v81, 31, v80
	v_lshlrev_b64 v[80:81], 10, v[80:81]
	v_lshl_add_u64 v[80:81], v[96:97], 0, v[80:81]
	global_store_short v[80:81], v82, off
	v_or_b32_e32 v80, 3, v100
	v_sub_u32_e32 v81, 63, v80
	v_cndmask_b32_e64 v80, v81, v80, s[2:3]
	v_ashrrev_i32_e32 v81, 31, v80
	v_lshlrev_b64 v[80:81], 10, v[80:81]
	v_cvt_pk_bf16_f32 v82, v83, s0
	v_lshl_add_u64 v[80:81], v[96:97], 0, v[80:81]
	global_store_short v[80:81], v82, off
	v_add_u32_e32 v80, 8, v100
	v_sub_u32_e32 v81, 55, v100
	v_cndmask_b32_e64 v80, v81, v80, s[2:3]
	v_ashrrev_i32_e32 v81, 31, v80
	v_lshlrev_b64 v[80:81], 10, v[80:81]
	v_cvt_pk_bf16_f32 v82, v84, s0
	v_lshl_add_u64 v[80:81], v[96:97], 0, v[80:81]
	global_store_short v[80:81], v82, off
	v_add_u32_e32 v80, 9, v100
	v_sub_u32_e32 v81, 54, v100
	v_cndmask_b32_e64 v80, v81, v80, s[2:3]
	v_ashrrev_i32_e32 v81, 31, v80
	v_lshlrev_b64 v[80:81], 10, v[80:81]
	v_cvt_pk_bf16_f32 v82, v85, s0
	v_lshl_add_u64 v[80:81], v[96:97], 0, v[80:81]
	global_store_short v[80:81], v82, off
	v_add_u32_e32 v80, 10, v100
	v_sub_u32_e32 v81, 53, v100
	v_cndmask_b32_e64 v80, v81, v80, s[2:3]
	v_ashrrev_i32_e32 v81, 31, v80
	v_lshlrev_b64 v[80:81], 10, v[80:81]
	v_cvt_pk_bf16_f32 v82, v86, s0
	v_lshl_add_u64 v[80:81], v[96:97], 0, v[80:81]
	global_store_short v[80:81], v82, off
	v_add_u32_e32 v80, 11, v100
	v_sub_u32_e32 v81, 52, v100
	v_cndmask_b32_e64 v80, v81, v80, s[2:3]
	v_ashrrev_i32_e32 v81, 31, v80
	v_lshlrev_b64 v[80:81], 10, v[80:81]
	v_cvt_pk_bf16_f32 v82, v87, s0
	v_lshl_add_u64 v[80:81], v[96:97], 0, v[80:81]
	global_store_short v[80:81], v82, off
	v_add_u32_e32 v80, 16, v100
	v_sub_u32_e32 v81, 47, v100
	v_cndmask_b32_e64 v80, v81, v80, s[2:3]
	v_ashrrev_i32_e32 v81, 31, v80
	v_lshlrev_b64 v[80:81], 10, v[80:81]
	v_cvt_pk_bf16_f32 v82, v88, s0
	v_lshl_add_u64 v[80:81], v[96:97], 0, v[80:81]
	global_store_short v[80:81], v82, off
	v_add_u32_e32 v80, 17, v100
	v_sub_u32_e32 v81, 46, v100
	v_cndmask_b32_e64 v80, v81, v80, s[2:3]
	v_ashrrev_i32_e32 v81, 31, v80
	v_lshlrev_b64 v[80:81], 10, v[80:81]
	v_cvt_pk_bf16_f32 v82, v89, s0
	v_lshl_add_u64 v[80:81], v[96:97], 0, v[80:81]
	global_store_short v[80:81], v82, off
	v_add_u32_e32 v80, 18, v100
	v_sub_u32_e32 v81, 45, v100
	v_cndmask_b32_e64 v80, v81, v80, s[2:3]
	v_ashrrev_i32_e32 v81, 31, v80
	v_lshlrev_b64 v[80:81], 10, v[80:81]
	v_cvt_pk_bf16_f32 v82, v90, s0
	v_lshl_add_u64 v[80:81], v[96:97], 0, v[80:81]
	global_store_short v[80:81], v82, off
	v_add_u32_e32 v80, 19, v100
	v_sub_u32_e32 v81, 44, v100
	v_cndmask_b32_e64 v80, v81, v80, s[2:3]
	v_ashrrev_i32_e32 v81, 31, v80
	v_lshlrev_b64 v[80:81], 10, v[80:81]
	v_cvt_pk_bf16_f32 v82, v91, s0
	v_lshl_add_u64 v[80:81], v[96:97], 0, v[80:81]
	global_store_short v[80:81], v82, off
	v_add_u32_e32 v80, 24, v100
	v_sub_u32_e32 v81, 39, v100
	v_cndmask_b32_e64 v80, v81, v80, s[2:3]
	v_ashrrev_i32_e32 v81, 31, v80
	v_lshlrev_b64 v[80:81], 10, v[80:81]
	v_cvt_pk_bf16_f32 v82, v92, s0
	v_lshl_add_u64 v[80:81], v[96:97], 0, v[80:81]
	global_store_short v[80:81], v82, off
	v_add_u32_e32 v80, 25, v100
	v_sub_u32_e32 v81, 38, v100
	v_cndmask_b32_e64 v80, v81, v80, s[2:3]
	v_ashrrev_i32_e32 v81, 31, v80
	v_lshlrev_b64 v[80:81], 10, v[80:81]
	v_cvt_pk_bf16_f32 v82, v93, s0
	v_lshl_add_u64 v[80:81], v[96:97], 0, v[80:81]
	global_store_short v[80:81], v82, off
	v_add_u32_e32 v80, 26, v100
	v_sub_u32_e32 v81, 37, v100
	v_cndmask_b32_e64 v80, v81, v80, s[2:3]
	v_ashrrev_i32_e32 v81, 31, v80
	v_lshlrev_b64 v[80:81], 10, v[80:81]
	v_cvt_pk_bf16_f32 v82, v94, s0
	v_lshl_add_u64 v[80:81], v[96:97], 0, v[80:81]
	global_store_short v[80:81], v82, off
	v_add_u32_e32 v80, 27, v100
	v_sub_u32_e32 v81, 36, v100
	v_cndmask_b32_e64 v80, v81, v80, s[2:3]
	v_ashrrev_i32_e32 v81, 31, v80
	v_lshlrev_b64 v[80:81], 10, v[80:81]
	v_cvt_pk_bf16_f32 v82, v95, s0
	v_lshl_add_u64 v[80:81], v[96:97], 0, v[80:81]
	global_store_short v[80:81], v82, off
	v_add_u32_e32 v80, 32, v100
	v_sub_u32_e32 v81, 31, v100
	v_cndmask_b32_e64 v80, v81, v80, s[2:3]
	v_ashrrev_i32_e32 v81, 31, v80
	v_lshlrev_b64 v[80:81], 10, v[80:81]
; DI bf16_t f2bf(float x) { return (bf16_t)(cvtpk(x, 0.f) & 0xffffu); }
; DI int crow(int r, int hi) { return (r & 3) + 8 * (r >> 2) + 4 * hi; }
; DI void dn_scan_item(const Params& p, int seqbase, int T, int h, int dir, char* lds) {
;     ...
;         const int cn = dir ? N - 1 - n : n; const size_t mrow0 = (size_t)(gch0 + cn) * 64;
; #pragma unroll
;         for (int pt = 0; pt < 2; ++pt)
; #pragma unroll
;             for (int i = 0; i < 16; ++i) {
;                 const int pi = pt * 32 + crow(i, hh), tl = dir ? 63 - pi : pi;
;                 Oout[(mrow0 + tl) * 512 + h * 128 + slab * 32 + r32] = f2bf(o[pt][i]);
;             }
	v_lshl_add_u64 v[80:81], v[96:97], 0, v[80:81]
	global_store_short v[80:81], v64, off
	v_add_u32_e32 v64, 33, v100
	v_sub_u32_e32 v80, 30, v100
	v_cndmask_b32_e64 v64, v80, v64, s[2:3]
	v_cvt_pk_bf16_f32 v80, v65, s0
	v_ashrrev_i32_e32 v65, 31, v64
	v_lshlrev_b64 v[64:65], 10, v[64:65]
	v_lshl_add_u64 v[64:65], v[96:97], 0, v[64:65]
	global_store_short v[64:65], v80, off
	v_add_u32_e32 v64, 34, v100
	v_sub_u32_e32 v65, 29, v100
	v_cndmask_b32_e64 v64, v65, v64, s[2:3]
	v_ashrrev_i32_e32 v65, 31, v64
	v_lshlrev_b64 v[64:65], 10, v[64:65]
	v_lshl_add_u64 v[64:65], v[96:97], 0, v[64:65]
	global_store_short v[64:65], v66, off
	v_add_u32_e32 v64, 35, v100
	v_sub_u32_e32 v65, 28, v100
	v_cndmask_b32_e64 v64, v65, v64, s[2:3]
	v_ashrrev_i32_e32 v65, 31, v64
	v_lshlrev_b64 v[64:65], 10, v[64:65]
	v_cvt_pk_bf16_f32 v66, v67, s0
	v_lshl_add_u64 v[64:65], v[96:97], 0, v[64:65]
	global_store_short v[64:65], v66, off
	v_add_u32_e32 v64, 40, v100
	v_sub_u32_e32 v65, 23, v100
	v_cndmask_b32_e64 v64, v65, v64, s[2:3]
	v_ashrrev_i32_e32 v65, 31, v64
	v_lshlrev_b64 v[64:65], 10, v[64:65]
	v_cvt_pk_bf16_f32 v66, v68, s0
	v_lshl_add_u64 v[64:65], v[96:97], 0, v[64:65]
	global_store_short v[64:65], v66, off
	v_add_u32_e32 v64, 41, v100
	v_sub_u32_e32 v65, 22, v100
	v_cndmask_b32_e64 v64, v65, v64, s[2:3]
	v_ashrrev_i32_e32 v65, 31, v64
	v_lshlrev_b64 v[64:65], 10, v[64:65]
	v_cvt_pk_bf16_f32 v66, v69, s0
	v_lshl_add_u64 v[64:65], v[96:97], 0, v[64:65]
	global_store_short v[64:65], v66, off
	v_add_u32_e32 v64, 42, v100
	v_sub_u32_e32 v65, 21, v100
	v_cndmask_b32_e64 v64, v65, v64, s[2:3]
	v_ashrrev_i32_e32 v65, 31, v64
	v_lshlrev_b64 v[64:65], 10, v[64:65]
	v_cvt_pk_bf16_f32 v66, v70, s0
	v_lshl_add_u64 v[64:65], v[96:97], 0, v[64:65]
	global_store_short v[64:65], v66, off
	v_add_u32_e32 v64, 43, v100
	v_sub_u32_e32 v65, 20, v100
	v_cndmask_b32_e64 v64, v65, v64, s[2:3]
	v_ashrrev_i32_e32 v65, 31, v64
	v_lshlrev_b64 v[64:65], 10, v[64:65]
	v_cvt_pk_bf16_f32 v66, v71, s0
	v_lshl_add_u64 v[64:65], v[96:97], 0, v[64:65]
	global_store_short v[64:65], v66, off
	v_add_u32_e32 v64, 48, v100
	v_sub_u32_e32 v65, 15, v100
	v_cndmask_b32_e64 v64, v65, v64, s[2:3]
	v_ashrrev_i32_e32 v65, 31, v64
	v_lshlrev_b64 v[64:65], 10, v[64:65]
	v_cvt_pk_bf16_f32 v66, v72, s0
	v_lshl_add_u64 v[64:65], v[96:97], 0, v[64:65]
	global_store_short v[64:65], v66, off
	v_add_u32_e32 v64, 49, v100
	v_sub_u32_e32 v65, 14, v100
	v_cndmask_b32_e64 v64, v65, v64, s[2:3]
	v_ashrrev_i32_e32 v65, 31, v64
	v_lshlrev_b64 v[64:65], 10, v[64:65]
	v_cvt_pk_bf16_f32 v66, v73, s0
	v_lshl_add_u64 v[64:65], v[96:97], 0, v[64:65]
	global_store_short v[64:65], v66, off
	v_add_u32_e32 v64, 50, v100
	v_sub_u32_e32 v65, 13, v100
	v_cndmask_b32_e64 v64, v65, v64, s[2:3]
	v_ashrrev_i32_e32 v65, 31, v64
	v_lshlrev_b64 v[64:65], 10, v[64:65]
	v_cvt_pk_bf16_f32 v66, v74, s0
	v_lshl_add_u64 v[64:65], v[96:97], 0, v[64:65]
	global_store_short v[64:65], v66, off
	v_add_u32_e32 v64, 51, v100
	v_sub_u32_e32 v65, 12, v100
	v_cndmask_b32_e64 v64, v65, v64, s[2:3]
	v_ashrrev_i32_e32 v65, 31, v64
	v_lshlrev_b64 v[64:65], 10, v[64:65]
	v_cvt_pk_bf16_f32 v66, v75, s0
	v_lshl_add_u64 v[64:65], v[96:97], 0, v[64:65]
	global_store_short v[64:65], v66, off
	v_add_u32_e32 v64, 56, v100
	v_sub_u32_e32 v65, 7, v100
	v_cndmask_b32_e64 v64, v65, v64, s[2:3]
	v_ashrrev_i32_e32 v65, 31, v64
	v_lshlrev_b64 v[64:65], 10, v[64:65]
	v_cvt_pk_bf16_f32 v66, v76, s0
	v_lshl_add_u64 v[64:65], v[96:97], 0, v[64:65]
	global_store_short v[64:65], v66, off
	v_add_u32_e32 v64, 57, v100
	v_sub_u32_e32 v65, 6, v100
	v_cndmask_b32_e64 v64, v65, v64, s[2:3]
	v_ashrrev_i32_e32 v65, 31, v64
	v_lshlrev_b64 v[64:65], 10, v[64:65]
	v_cvt_pk_bf16_f32 v66, v77, s0
	v_lshl_add_u64 v[64:65], v[96:97], 0, v[64:65]
	global_store_short v[64:65], v66, off
	v_add_u32_e32 v64, 58, v100
	v_sub_u32_e32 v65, 5, v100
	v_cndmask_b32_e64 v64, v65, v64, s[2:3]
	v_ashrrev_i32_e32 v65, 31, v64
	v_lshlrev_b64 v[64:65], 10, v[64:65]
	v_cvt_pk_bf16_f32 v66, v78, s0
	v_lshl_add_u64 v[64:65], v[96:97], 0, v[64:65]
	global_store_short v[64:65], v66, off
	v_add_u32_e32 v64, 59, v100
	v_sub_u32_e32 v65, 4, v100
	v_cndmask_b32_e64 v64, v65, v64, s[2:3]
	v_ashrrev_i32_e32 v65, 31, v64
	v_lshlrev_b64 v[64:65], 10, v[64:65]
	v_cvt_pk_bf16_f32 v66, v79, s0
	v_lshl_add_u64 v[64:65], v[96:97], 0, v[64:65]
	global_store_short v[64:65], v66, off
	v_mov_b64_e32 v[144:145], v[168:169]
	v_mov_b64_e32 v[76:77], v[132:133]
	v_mov_b64_e32 v[72:73], v[128:129]
	v_mov_b64_e32 v[68:69], v[140:141]
	v_mov_b64_e32 v[64:65], v[136:137]
	v_mov_b64_e32 v[146:147], v[170:171]
	v_mov_b64_e32 v[78:79], v[134:135]
	v_mov_b64_e32 v[74:75], v[130:131]
	v_mov_b64_e32 v[70:71], v[142:143]
	v_mov_b64_e32 v[66:67], v[138:139]
	v_mov_b32_e32 v80, v205
	s_barrier
	s_cbranch_scc1 .LBB0_629

; #define MFMA32(a, b, c) __builtin_amdgcn_mfma_f32_32x32x16_bf16((a), (b), (c), 0, 0, 0)
; DI float bflo(unsigned w) { return __uint_as_float(w << 16); }
; DI float bfhi(unsigned w) { return __uint_as_float(w & 0xffff0000u); }
; DI void dn_scan_item(const Params& p, int seqbase, int T, int h, int dir, char* lds) {
;     ...
;     auto compute = [&](int n, int par, URegs& U) {
;         int lane = lane0; asm volatile("" : "+v"(lane));
;         const int r32 = lane & 31, hh = lane >> 5;
;         const char* buf = lds + par * SL_BUF;
;         f32x16 vn[2], o[2];
; #pragma unroll
;         for (int pt = 0; pt < 2; ++pt) {
;             const unsigned uu[8] = {U.un[pt][0].x, U.un[pt][0].y, U.un[pt][0].z, U.un[pt][0].w, U.un[pt][1].x, U.un[pt][1].y, U.un[pt][1].z, U.un[pt][1].w};
; #pragma unroll
;             for (int e = 0; e < 8; ++e) { vn[pt][2 * e] = bflo(uu[e]); vn[pt][2 * e + 1] = bfhi(uu[e]); }
; #pragma unroll
;             for (int i = 0; i < 16; ++i) o[pt][i] = 0.f;
;         }
;         const float gl = __expf(U.gl);
;         if (n + 2 < N) uload(n + 2, U);
; #pragma unroll
;         for (int ks = 0; ks < 8; ++ks) {
;             const bf16x8 sb = pack8(S[ks >> 1], ks & 1);
;             const int off = (ks * 16 + 4 * hh) * 2;
; #pragma unroll
;             for (int pt = 0; pt < 2; ++pt) {
;                 const char* wr = buf + SL_W + (pt * 32 + r32) * 264 + off;
;                 const char* qr = buf + SL_QG + (pt * 32 + r32) * 264 + off;
;                 vn[pt] = MFMA32(ld2x64(wr, wr + 16), sb, vn[pt]);
;                 o[pt] = MFMA32(ld2x64(qr, qr + 16), sb, o[pt]);
;             }
;         }
.LBB0_627:
	v_ashrrev_i32_e32 v162, 5, v81
	v_and_b32_e32 v161, 31, v81
	v_lshl_add_u32 v163, v162, 3, 0
	v_mad_u32_u24 v165, v161, s88, v163
	v_lshlrev_b32_e32 v112, 16, v68
	v_and_b32_e32 v113, 0xffff0000, v68
	v_lshlrev_b32_e32 v114, 16, v69
	v_and_b32_e32 v115, 0xffff0000, v69
	v_lshlrev_b32_e32 v116, 16, v70
	v_and_b32_e32 v117, 0xffff0000, v70
	v_lshlrev_b32_e32 v118, 16, v71
	v_and_b32_e32 v119, 0xffff0000, v71
	ds_read2_b64 v[68:71], v165 offset1:2
	ds_read2_b64 v[168:171], v165 offset0:4 offset1:6
	v_lshlrev_b32_e32 v120, 16, v64
	v_and_b32_e32 v121, 0xffff0000, v64
	v_mul_f32_e32 v64, 0x3fb8aa3b, v80
	v_lshlrev_b32_e32 v96, 16, v76
	v_and_b32_e32 v97, 0xffff0000, v76
	v_lshlrev_b32_e32 v98, 16, v77
	v_and_b32_e32 v99, 0xffff0000, v77
	v_lshlrev_b32_e32 v100, 16, v78
	v_and_b32_e32 v101, 0xffff0000, v78
	v_lshlrev_b32_e32 v102, 16, v79
	v_and_b32_e32 v103, 0xffff0000, v79
	v_lshlrev_b32_e32 v104, 16, v72
	v_and_b32_e32 v105, 0xffff0000, v72
	v_lshlrev_b32_e32 v106, 16, v73
	v_and_b32_e32 v107, 0xffff0000, v73
	v_lshlrev_b32_e32 v108, 16, v74
	v_and_b32_e32 v109, 0xffff0000, v74
	v_lshlrev_b32_e32 v110, 16, v75
	v_and_b32_e32 v111, 0xffff0000, v75
	v_lshlrev_b32_e32 v122, 16, v65
	v_and_b32_e32 v123, 0xffff0000, v65
	v_lshlrev_b32_e32 v124, 16, v66
	v_and_b32_e32 v125, 0xffff0000, v66
	v_lshlrev_b32_e32 v126, 16, v67
	v_and_b32_e32 v127, 0xffff0000, v67
	v_exp_f32_e32 v160, v64
	v_cvt_pk_bf16_f32 v64, v48, v49
	v_cvt_pk_bf16_f32 v65, v50, v51
	v_cvt_pk_bf16_f32 v66, v52, v53
	v_cvt_pk_bf16_f32 v67, v54, v55
	v_add_u32_e32 v164, 0x4000, v165
	v_cvt_pk_bf16_f32 v172, v56, v57
	s_waitcnt lgkmcnt(1)
	v_mfma_f32_32x32x16_bf16 v[96:111], v[68:71], v[64:67], v[96:111]
	ds_read2_b64 v[68:71], v164 offset0:64 offset1:66
	v_cvt_pk_bf16_f32 v173, v58, v59
	v_cvt_pk_bf16_f32 v174, v60, v61
	v_cvt_pk_bf16_f32 v175, v62, v63
	v_add_u32_e32 v166, 0x2000, v165
	v_add_u32_e32 v167, 0x6000, v165
	v_pk_mul_f32 v[62:63], v[62:63], v[160:161] op_sel_hi:[1,0]
	s_waitcnt lgkmcnt(1)
	v_mfma_f32_32x32x16_bf16 v[96:111], v[168:171], v[172:175], v[96:111]
	ds_read2_b64 v[168:171], v164 offset0:68 offset1:70
	v_mul_f32_e64 v60, v60, v160
	v_mul_f32_e64 v61, v61, v160
	v_mul_f32_e64 v58, v58, v160
	v_mul_f32_e64 v59, v59, v160
	v_pk_mul_f32 v[56:57], v[56:57], v[160:161] op_sel_hi:[1,0]
	v_pk_mul_f32 v[54:55], v[54:55], v[160:161] op_sel_hi:[1,0]
	v_pk_mul_f32 v[52:53], v[52:53], v[160:161] op_sel_hi:[1,0]
	v_pk_mul_f32 v[50:51], v[50:51], v[160:161] op_sel_hi:[1,0]
	s_waitcnt lgkmcnt(1)
	v_mfma_f32_32x32x16_bf16 v[80:95], v[68:71], v[64:67], 0
	ds_read2_b64 v[68:71], v166 offset0:32 offset1:34
	v_mul_f32_e64 v48, v48, v160
	v_mul_f32_e64 v49, v49, v160
	s_and_b64 s[22:23], s[2:3], exec
	s_cselect_b32 s21, s20, s14
	s_add_i32 s22, s21, s25
	s_ashr_i32 s23, s22, 31
	s_lshl_b64 s[22:23], s[22:23], 16
	s_waitcnt lgkmcnt(1)
	v_mfma_f32_32x32x16_bf16 v[80:95], v[168:171], v[172:175], v[80:95]
	ds_read2_b64 v[168:171], v166 offset0:36 offset1:38
	s_add_u32 s22, s17, s22
	s_addc_u32 s23, s18, s23
	v_lshlrev_b32_e32 v184, 1, v161
	s_cmpk_gt_u32 s20, 0xfc
	v_mov_b32_e32 v207, v206
	s_waitcnt lgkmcnt(1)
	v_mfma_f32_32x32x16_bf16 v[112:127], v[68:71], v[64:67], v[112:127]
	ds_read2_b64 v[68:71], v167 offset0:96 offset1:98
	s_waitcnt lgkmcnt(1)
	v_mfma_f32_32x32x16_bf16 v[112:127], v[168:171], v[172:175], v[112:127]
	ds_read2_b64 v[168:171], v167 offset0:100 offset1:102
	s_waitcnt lgkmcnt(1)
	v_mfma_f32_32x32x16_bf16 v[64:79], v[68:71], v[64:67], 0
	s_waitcnt lgkmcnt(0)
	v_mfma_f32_32x32x16_bf16 v[64:79], v[168:171], v[172:175], v[64:79]
	ds_read2_b64 v[172:175], v165 offset0:8 offset1:10
	v_cvt_pk_bf16_f32 v168, v32, v33
	v_cvt_pk_bf16_f32 v169, v34, v35
	v_cvt_pk_bf16_f32 v170, v36, v37
	v_cvt_pk_bf16_f32 v171, v38, v39
	v_pk_mul_f32 v[38:39], v[38:39], v[160:161] op_sel_hi:[1,0]
	v_pk_mul_f32 v[36:37], v[36:37], v[160:161] op_sel_hi:[1,0]
	s_waitcnt lgkmcnt(0)
	v_mfma_f32_32x32x16_bf16 v[96:111], v[172:175], v[168:171], v[96:111]
	ds_read2_b64 v[172:175], v164 offset0:72 offset1:74
	v_mul_f32_e64 v34, v34, v160
	v_mul_f32_e64 v35, v35, v160
	v_mul_f32_e64 v32, v32, v160
	v_mul_f32_e64 v33, v33, v160
	s_waitcnt lgkmcnt(0)
	v_mfma_f32_32x32x16_bf16 v[80:95], v[172:175], v[168:171], v[80:95]
	ds_read2_b64 v[172:175], v166 offset0:40 offset1:42
	s_waitcnt lgkmcnt(0)
	v_mfma_f32_32x32x16_bf16 v[112:127], v[172:175], v[168:171], v[112:127]
	ds_read2_b64 v[172:175], v167 offset0:104 offset1:106
	s_waitcnt lgkmcnt(0)
	v_mfma_f32_32x32x16_bf16 v[64:79], v[172:175], v[168:171], v[64:79]
	ds_read2_b64 v[172:175], v165 offset0:12 offset1:14
	v_cvt_pk_bf16_f32 v168, v40, v41
	v_cvt_pk_bf16_f32 v169, v42, v43
	v_cvt_pk_bf16_f32 v170, v44, v45
	v_cvt_pk_bf16_f32 v171, v46, v47
	v_pk_mul_f32 v[46:47], v[46:47], v[160:161] op_sel_hi:[1,0]
	v_pk_mul_f32 v[44:45], v[44:45], v[160:161] op_sel_hi:[1,0]
	s_waitcnt lgkmcnt(0)
	v_mfma_f32_32x32x16_bf16 v[96:111], v[172:175], v[168:171], v[96:111]
	ds_read2_b64 v[172:175], v164 offset0:76 offset1:78
	v_mul_f32_e64 v42, v42, v160
	v_mul_f32_e64 v43, v43, v160
	v_mul_f32_e64 v40, v40, v160
	v_mul_f32_e64 v41, v41, v160
	s_waitcnt lgkmcnt(0)
	v_mfma_f32_32x32x16_bf16 v[80:95], v[172:175], v[168:171], v[80:95]
	ds_read2_b64 v[172:175], v166 offset0:44 offset1:46
	s_waitcnt lgkmcnt(0)
	v_mfma_f32_32x32x16_bf16 v[112:127], v[172:175], v[168:171], v[112:127]
	ds_read2_b64 v[172:175], v167 offset0:108 offset1:110
	s_waitcnt lgkmcnt(0)
	v_mfma_f32_32x32x16_bf16 v[64:79], v[172:175], v[168:171], v[64:79]
	ds_read2_b64 v[172:175], v165 offset0:16 offset1:18
	v_cvt_pk_bf16_f32 v168, v16, v17
	v_cvt_pk_bf16_f32 v169, v18, v19
	v_cvt_pk_bf16_f32 v170, v20, v21
	v_cvt_pk_bf16_f32 v171, v22, v23
	v_pk_mul_f32 v[22:23], v[22:23], v[160:161] op_sel_hi:[1,0]
	v_pk_mul_f32 v[20:21], v[20:21], v[160:161] op_sel_hi:[1,0]
	s_waitcnt lgkmcnt(0)
; #define MFMA32(a, b, c) __builtin_amdgcn_mfma_f32_32x32x16_bf16((a), (b), (c), 0, 0, 0)
; DI void dn_scan_item(const Params& p, int seqbase, int T, int h, int dir, char* lds) {
;     ...
; #pragma unroll
;         for (int ks = 0; ks < 8; ++ks) {
;             const bf16x8 sb = pack8(S[ks >> 1], ks & 1);
;             const int off = (ks * 16 + 4 * hh) * 2;
; #pragma unroll
;             for (int pt = 0; pt < 2; ++pt) {
;                 const char* wr = buf + SL_W + (pt * 32 + r32) * 264 + off;
;                 const char* qr = buf + SL_QG + (pt * 32 + r32) * 264 + off;
;                 vn[pt] = MFMA32(ld2x64(wr, wr + 16), sb, vn[pt]);
;                 o[pt] = MFMA32(ld2x64(qr, qr + 16), sb, o[pt]);
;             }
;         }
;         bf16x8 vb[4];
; #pragma unroll
;         for (int kp = 0; kp < 4; ++kp) vb[kp] = pack8(vn[kp >> 1], kp & 1);
; #pragma unroll
;         for (int d = 0; d < 4; ++d) S[d] = S[d] * gl;
; #pragma unroll
;         for (int kp = 0; kp < 4; ++kp) {
;             const int off = (kp * 16 + 4 * hh) * 2;
; #pragma unroll
;             for (int pt = 0; pt < 2; ++pt) { const char* ar = buf + SL_AT + (pt * 32 + r32) * 136 + off; o[pt] = MFMA32(ld2x64(ar, ar + 16), vb[kp], o[pt]); }
; #pragma unroll
;             for (int d = 0; d < 4; ++d) { const char* kr = buf + SL_KDT + (d * 32 + r32) * 136 + off; S[d] = MFMA32(ld2x64(kr, kr + 16), vb[kp], S[d]); }
	v_mfma_f32_32x32x16_bf16 v[96:111], v[172:175], v[168:171], v[96:111]
	ds_read2_b64 v[172:175], v164 offset0:80 offset1:82
	v_mul_f32_e64 v18, v18, v160
	v_mul_f32_e64 v19, v19, v160
	v_mul_f32_e64 v16, v16, v160
	v_mul_f32_e64 v17, v17, v160
	s_waitcnt lgkmcnt(0)
	v_mfma_f32_32x32x16_bf16 v[80:95], v[172:175], v[168:171], v[80:95]
	ds_read2_b64 v[172:175], v166 offset0:48 offset1:50
	s_waitcnt lgkmcnt(0)
	v_mfma_f32_32x32x16_bf16 v[112:127], v[172:175], v[168:171], v[112:127]
	ds_read2_b64 v[172:175], v167 offset0:112 offset1:114
	s_waitcnt lgkmcnt(0)
	v_mfma_f32_32x32x16_bf16 v[64:79], v[172:175], v[168:171], v[64:79]
	ds_read2_b64 v[172:175], v165 offset0:20 offset1:22
	v_cvt_pk_bf16_f32 v168, v24, v25
	v_cvt_pk_bf16_f32 v169, v26, v27
	v_cvt_pk_bf16_f32 v170, v28, v29
	v_cvt_pk_bf16_f32 v171, v30, v31
	v_pk_mul_f32 v[30:31], v[30:31], v[160:161] op_sel_hi:[1,0]
	v_pk_mul_f32 v[28:29], v[28:29], v[160:161] op_sel_hi:[1,0]
	s_waitcnt lgkmcnt(0)
	v_mfma_f32_32x32x16_bf16 v[96:111], v[172:175], v[168:171], v[96:111]
	ds_read2_b64 v[172:175], v164 offset0:84 offset1:86
	v_mul_f32_e64 v26, v26, v160
	v_mul_f32_e64 v27, v27, v160
	v_mul_f32_e64 v24, v24, v160
	v_mul_f32_e64 v25, v25, v160
	s_waitcnt lgkmcnt(0)
	v_mfma_f32_32x32x16_bf16 v[80:95], v[172:175], v[168:171], v[80:95]
	ds_read2_b64 v[172:175], v166 offset0:52 offset1:54
	s_waitcnt lgkmcnt(0)
	v_mfma_f32_32x32x16_bf16 v[112:127], v[172:175], v[168:171], v[112:127]
	ds_read2_b64 v[172:175], v167 offset0:116 offset1:118
	s_waitcnt lgkmcnt(0)
	v_mfma_f32_32x32x16_bf16 v[64:79], v[172:175], v[168:171], v[64:79]
	ds_read2_b64 v[172:175], v165 offset0:24 offset1:26
	v_cvt_pk_bf16_f32 v168, v0, v1
	v_cvt_pk_bf16_f32 v169, v2, v3
	v_cvt_pk_bf16_f32 v170, v4, v5
	v_cvt_pk_bf16_f32 v171, v6, v7
	v_pk_mul_f32 v[6:7], v[6:7], v[160:161] op_sel_hi:[1,0]
	v_pk_mul_f32 v[4:5], v[4:5], v[160:161] op_sel_hi:[1,0]
	s_waitcnt lgkmcnt(0)
	v_mfma_f32_32x32x16_bf16 v[96:111], v[172:175], v[168:171], v[96:111]
	ds_read2_b64 v[172:175], v164 offset0:88 offset1:90
	v_mul_f32_e64 v2, v2, v160
	v_mul_f32_e64 v3, v3, v160
	v_mul_f32_e64 v0, v0, v160
	v_mul_f32_e64 v1, v1, v160
	s_waitcnt lgkmcnt(0)
	v_mfma_f32_32x32x16_bf16 v[80:95], v[172:175], v[168:171], v[80:95]
	ds_read2_b64 v[172:175], v166 offset0:56 offset1:58
	s_waitcnt lgkmcnt(0)
	v_mfma_f32_32x32x16_bf16 v[112:127], v[172:175], v[168:171], v[112:127]
	ds_read2_b64 v[172:175], v167 offset0:120 offset1:122
	s_waitcnt lgkmcnt(0)
	v_mfma_f32_32x32x16_bf16 v[64:79], v[172:175], v[168:171], v[64:79]
	ds_read2_b64 v[172:175], v165 offset0:28 offset1:30
	v_cvt_pk_bf16_f32 v168, v8, v9
	v_cvt_pk_bf16_f32 v169, v10, v11
	v_cvt_pk_bf16_f32 v170, v12, v13
	v_cvt_pk_bf16_f32 v171, v14, v15
	v_pk_mul_f32 v[14:15], v[14:15], v[160:161] op_sel_hi:[1,0]
	v_pk_mul_f32 v[12:13], v[12:13], v[160:161] op_sel_hi:[1,0]
	s_waitcnt lgkmcnt(0)
	v_mfma_f32_32x32x16_bf16 v[96:111], v[172:175], v[168:171], v[96:111]
	ds_read2_b64 v[172:175], v164 offset0:92 offset1:94
	v_mul_f32_e64 v10, v10, v160
	v_mul_f32_e64 v11, v11, v160
	v_mul_f32_e64 v8, v8, v160
	v_mul_f32_e64 v9, v9, v160
	s_nop 6
	v_cvt_pk_bf16_f32 v104, v104, v105
	s_waitcnt lgkmcnt(0)
	v_mfma_f32_32x32x16_bf16 v[80:95], v[172:175], v[168:171], v[80:95]
	ds_read2_b64 v[172:175], v166 offset0:60 offset1:62
	ds_read2_b64 v[164:167], v167 offset0:124 offset1:126
	v_cvt_pk_bf16_f32 v105, v106, v107
	v_cvt_pk_bf16_f32 v106, v108, v109
	v_cvt_pk_bf16_f32 v107, v110, v111
	s_waitcnt lgkmcnt(1)
	v_mfma_f32_32x32x16_bf16 v[112:127], v[172:175], v[168:171], v[112:127]
	v_mov_b64_e32 v[174:175], v[150:151]
	v_mov_b64_e32 v[172:173], v[148:149]
	s_waitcnt lgkmcnt(0)
	v_mfma_f32_32x32x16_bf16 v[64:79], v[164:167], v[168:171], v[64:79]
	v_cvt_pk_bf16_f32 v167, v102, v103
	s_nop 6
	v_cvt_pk_bf16_f32 v102, v116, v117
	v_mad_u32_u24 v116, v161, s89, v163
	v_add_u32_e32 v117, 0xc800, v116
	ds_read2_b64 v[108:111], v117 offset1:2
	v_cvt_pk_bf16_f32 v164, v96, v97
	v_cvt_pk_bf16_f32 v165, v98, v99
	v_cvt_pk_bf16_f32 v166, v100, v101
	v_cvt_pk_bf16_f32 v103, v118, v119
	v_add_u32_e32 v118, 0xd800, v116
	s_waitcnt lgkmcnt(0)
	v_mfma_f32_32x32x16_bf16 v[80:95], v[108:111], v[164:167], v[80:95]
	ds_read2_b64 v[108:111], v118 offset0:32 offset1:34
	v_add_u32_e32 v119, 0x8000, v116
	v_cvt_pk_bf16_f32 v100, v112, v113
	v_cvt_pk_bf16_f32 v101, v114, v115
	v_cvt_pk_bf16_f32 v96, v120, v121
	v_add_u32_e32 v120, 0x9000, v116
	v_add_u32_e32 v121, 0xa000, v116
	s_waitcnt lgkmcnt(0)
	v_mfma_f32_32x32x16_bf16 v[64:79], v[108:111], v[164:167], v[64:79]
	ds_read2_b64 v[108:111], v119 offset0:128 offset1:130
	ds_read2_b64 v[112:115], v119 offset0:132 offset1:134
	v_add_u32_e32 v116, 0xb000, v116
	v_cvt_pk_bf16_f32 v97, v122, v123
	v_cvt_pk_bf16_f32 v98, v124, v125
	v_cvt_pk_bf16_f32 v99, v126, v127
	v_mov_b64_e32 v[170:171], v[146:147]
	v_mov_b64_e32 v[168:169], v[144:145]
	s_waitcnt lgkmcnt(1)
	v_mfma_f32_32x32x16_bf16 v[48:63], v[108:111], v[164:167], v[48:63]
	ds_read2_b64 v[108:111], v120 offset0:160 offset1:162
	s_waitcnt lgkmcnt(0)
	v_mfma_f32_32x32x16_bf16 v[32:47], v[108:111], v[164:167], v[32:47]
	ds_read2_b64 v[108:111], v121 offset0:192 offset1:194
	s_waitcnt lgkmcnt(0)
	v_mfma_f32_32x32x16_bf16 v[16:31], v[108:111], v[164:167], v[16:31]
	ds_read2_b64 v[108:111], v116 offset0:224 offset1:226
	s_waitcnt lgkmcnt(0)
	v_mfma_f32_32x32x16_bf16 v[0:15], v[108:111], v[164:167], v[0:15]
	ds_read2_b64 v[108:111], v117 offset0:4 offset1:6
	v_mov_b64_e32 v[166:167], v[158:159]
	v_mov_b64_e32 v[164:165], v[156:157]
	s_waitcnt lgkmcnt(0)
	v_mfma_f32_32x32x16_bf16 v[80:95], v[108:111], v[104:107], v[80:95]
	ds_read2_b64 v[108:111], v118 offset0:36 offset1:38
	s_waitcnt lgkmcnt(0)
; #define MFMA32(a, b, c) __builtin_amdgcn_mfma_f32_32x32x16_bf16((a), (b), (c), 0, 0, 0)
; DI bf16_t f2bf(float x) { return (bf16_t)(cvtpk(x, 0.f) & 0xffffu); }
; DI int crow(int r, int hi) { return (r & 3) + 8 * (r >> 2) + 4 * hi; }
; DI void dn_scan_item(const Params& p, int seqbase, int T, int h, int dir, char* lds) {
;     ...
;         for (int kp = 0; kp < 4; ++kp) {
;             const int off = (kp * 16 + 4 * hh) * 2;
; #pragma unroll
;             for (int pt = 0; pt < 2; ++pt) { const char* ar = buf + SL_AT + (pt * 32 + r32) * 136 + off; o[pt] = MFMA32(ld2x64(ar, ar + 16), vb[kp], o[pt]); }
; #pragma unroll
;             for (int d = 0; d < 4; ++d) { const char* kr = buf + SL_KDT + (d * 32 + r32) * 136 + off; S[d] = MFMA32(ld2x64(kr, kr + 16), vb[kp], S[d]); }
;         }
;         const int cn = dir ? N - 1 - n : n; const size_t mrow0 = (size_t)(gch0 + cn) * 64;
; #pragma unroll
;         for (int pt = 0; pt < 2; ++pt)
; #pragma unroll
;             for (int i = 0; i < 16; ++i) {
;                 const int pi = pt * 32 + crow(i, hh), tl = dir ? 63 - pi : pi;
;                 Oout[(mrow0 + tl) * 512 + h * 128 + slab * 32 + r32] = f2bf(o[pt][i]);
;             }
	v_mfma_f32_32x32x16_bf16 v[64:79], v[108:111], v[104:107], v[64:79]
	ds_read2_b64 v[108:111], v120 offset0:164 offset1:166
	s_waitcnt lgkmcnt(0)
	v_mfma_f32_32x32x16_bf16 v[32:47], v[108:111], v[104:107], v[32:47]
	ds_read2_b64 v[108:111], v121 offset0:196 offset1:198
	s_waitcnt lgkmcnt(0)
	v_mfma_f32_32x32x16_bf16 v[16:31], v[108:111], v[104:107], v[16:31]
	ds_read2_b64 v[108:111], v116 offset0:228 offset1:230
	v_mfma_f32_32x32x16_bf16 v[48:63], v[112:115], v[104:107], v[48:63]
	s_waitcnt lgkmcnt(0)
	v_mfma_f32_32x32x16_bf16 v[0:15], v[108:111], v[104:107], v[0:15]
	ds_read2_b64 v[104:107], v117 offset0:8 offset1:10
	s_waitcnt lgkmcnt(0)
	v_mfma_f32_32x32x16_bf16 v[80:95], v[104:107], v[100:103], v[80:95]
	ds_read2_b64 v[104:107], v118 offset0:40 offset1:42
	s_waitcnt lgkmcnt(0)
	v_mfma_f32_32x32x16_bf16 v[64:79], v[104:107], v[100:103], v[64:79]
	ds_read2_b64 v[104:107], v119 offset0:136 offset1:138
	s_waitcnt lgkmcnt(0)
	v_mfma_f32_32x32x16_bf16 v[48:63], v[104:107], v[100:103], v[48:63]
	ds_read2_b64 v[104:107], v120 offset0:168 offset1:170
	s_waitcnt lgkmcnt(0)
	v_mfma_f32_32x32x16_bf16 v[32:47], v[104:107], v[100:103], v[32:47]
	ds_read2_b64 v[104:107], v121 offset0:200 offset1:202
	s_waitcnt lgkmcnt(0)
	v_mfma_f32_32x32x16_bf16 v[16:31], v[104:107], v[100:103], v[16:31]
	ds_read2_b64 v[104:107], v116 offset0:232 offset1:234
	s_waitcnt lgkmcnt(0)
	v_mfma_f32_32x32x16_bf16 v[0:15], v[104:107], v[100:103], v[0:15]
	ds_read2_b64 v[100:103], v117 offset0:12 offset1:14
	s_waitcnt lgkmcnt(0)
	v_mfma_f32_32x32x16_bf16 v[80:95], v[100:103], v[96:99], v[80:95]
	ds_read2_b64 v[100:103], v118 offset0:44 offset1:46
	s_waitcnt lgkmcnt(0)
	v_mfma_f32_32x32x16_bf16 v[64:79], v[100:103], v[96:99], v[64:79]
	ds_read2_b64 v[100:103], v119 offset0:140 offset1:142
	s_nop 7
	v_cvt_pk_bf16_f32 v80, v80, s0
	v_cvt_pk_bf16_f32 v82, v82, s0
	s_nop 0
	v_cvt_pk_bf16_f32 v64, v64, s0
	s_waitcnt lgkmcnt(0)
	v_mfma_f32_32x32x16_bf16 v[48:63], v[100:103], v[96:99], v[48:63]
	ds_read2_b64 v[100:103], v120 offset0:172 offset1:174
	v_cvt_pk_bf16_f32 v66, v66, s0
	s_waitcnt lgkmcnt(0)
	v_mfma_f32_32x32x16_bf16 v[32:47], v[100:103], v[96:99], v[32:47]
	ds_read2_b64 v[100:103], v121 offset0:204 offset1:206
	s_waitcnt lgkmcnt(0)
	v_mfma_f32_32x32x16_bf16 v[16:31], v[100:103], v[96:99], v[16:31]
	ds_read2_b64 v[100:103], v116 offset0:236 offset1:238
	s_waitcnt lgkmcnt(0)
	v_mfma_f32_32x32x16_bf16 v[0:15], v[100:103], v[96:99], v[0:15]
	v_lshlrev_b32_e32 v100, 2, v162
	v_sub_u32_e32 v98, 63, v100
	v_cndmask_b32_e64 v98, v98, v100, s[2:3]
	v_ashrrev_i32_e32 v99, 31, v98
	v_lshl_add_u64 v[96:97], s[22:23], 0, v[184:185]
	v_lshlrev_b64 v[98:99], 10, v[98:99]
	v_lshl_add_u64 v[98:99], v[96:97], 0, v[98:99]
	s_waitcnt vmcnt(0)
	global_store_short v[98:99], v80, off
	v_or_b32_e32 v80, 1, v100
	v_sub_u32_e32 v98, 63, v80
	v_cndmask_b32_e64 v80, v98, v80, s[2:3]
	v_cvt_pk_bf16_f32 v98, v81, s0
	v_ashrrev_i32_e32 v81, 31, v80
	v_lshlrev_b64 v[80:81], 10, v[80:81]
	v_lshl_add_u64 v[80:81], v[96:97], 0, v[80:81]
	global_store_short v[80:81], v98, off
	v_or_b32_e32 v80, 2, v100
	v_sub_u32_e32 v81, 63, v80
	v_cndmask_b32_e64 v80, v81, v80, s[2:3]
	v_ashrrev_i32_e32 v81, 31, v80
	v_lshlrev_b64 v[80:81], 10, v[80:81]
	v_lshl_add_u64 v[80:81], v[96:97], 0, v[80:81]
	global_store_short v[80:81], v82, off
	v_or_b32_e32 v80, 3, v100
	v_sub_u32_e32 v81, 63, v80
	v_cndmask_b32_e64 v80, v81, v80, s[2:3]
	v_ashrrev_i32_e32 v81, 31, v80
	v_lshlrev_b64 v[80:81], 10, v[80:81]
	v_cvt_pk_bf16_f32 v82, v83, s0
	v_lshl_add_u64 v[80:81], v[96:97], 0, v[80:81]
	global_store_short v[80:81], v82, off
	v_add_u32_e32 v80, 8, v100
	v_sub_u32_e32 v81, 55, v100
	v_cndmask_b32_e64 v80, v81, v80, s[2:3]
	v_ashrrev_i32_e32 v81, 31, v80
	v_lshlrev_b64 v[80:81], 10, v[80:81]
	v_cvt_pk_bf16_f32 v82, v84, s0
	v_lshl_add_u64 v[80:81], v[96:97], 0, v[80:81]
	global_store_short v[80:81], v82, off
	v_add_u32_e32 v80, 9, v100
	v_sub_u32_e32 v81, 54, v100
	v_cndmask_b32_e64 v80, v81, v80, s[2:3]
	v_ashrrev_i32_e32 v81, 31, v80
	v_lshlrev_b64 v[80:81], 10, v[80:81]
	v_cvt_pk_bf16_f32 v82, v85, s0
	v_lshl_add_u64 v[80:81], v[96:97], 0, v[80:81]
	global_store_short v[80:81], v82, off
	v_add_u32_e32 v80, 10, v100
	v_sub_u32_e32 v81, 53, v100
	v_cndmask_b32_e64 v80, v81, v80, s[2:3]
	v_ashrrev_i32_e32 v81, 31, v80
	v_lshlrev_b64 v[80:81], 10, v[80:81]
	v_cvt_pk_bf16_f32 v82, v86, s0
	v_lshl_add_u64 v[80:81], v[96:97], 0, v[80:81]
	global_store_short v[80:81], v82, off
	v_add_u32_e32 v80, 11, v100
	v_sub_u32_e32 v81, 52, v100
	v_cndmask_b32_e64 v80, v81, v80, s[2:3]
	v_ashrrev_i32_e32 v81, 31, v80
	v_lshlrev_b64 v[80:81], 10, v[80:81]
	v_cvt_pk_bf16_f32 v82, v87, s0
	v_lshl_add_u64 v[80:81], v[96:97], 0, v[80:81]
	global_store_short v[80:81], v82, off
	v_add_u32_e32 v80, 16, v100
	v_sub_u32_e32 v81, 47, v100
	v_cndmask_b32_e64 v80, v81, v80, s[2:3]
	v_ashrrev_i32_e32 v81, 31, v80
	v_lshlrev_b64 v[80:81], 10, v[80:81]
	v_cvt_pk_bf16_f32 v82, v88, s0
	v_lshl_add_u64 v[80:81], v[96:97], 0, v[80:81]
	global_store_short v[80:81], v82, off
	v_add_u32_e32 v80, 17, v100
	v_sub_u32_e32 v81, 46, v100
	v_cndmask_b32_e64 v80, v81, v80, s[2:3]
	v_ashrrev_i32_e32 v81, 31, v80
	v_lshlrev_b64 v[80:81], 10, v[80:81]
	v_cvt_pk_bf16_f32 v82, v89, s0
	v_lshl_add_u64 v[80:81], v[96:97], 0, v[80:81]
	global_store_short v[80:81], v82, off
	v_add_u32_e32 v80, 18, v100
	v_sub_u32_e32 v81, 45, v100
	v_cndmask_b32_e64 v80, v81, v80, s[2:3]
	v_ashrrev_i32_e32 v81, 31, v80
	v_lshlrev_b64 v[80:81], 10, v[80:81]
	v_cvt_pk_bf16_f32 v82, v90, s0
	v_lshl_add_u64 v[80:81], v[96:97], 0, v[80:81]
	global_store_short v[80:81], v82, off
	v_add_u32_e32 v80, 19, v100
; DI bf16_t f2bf(float x) { return (bf16_t)(cvtpk(x, 0.f) & 0xffffu); }
; DI int crow(int r, int hi) { return (r & 3) + 8 * (r >> 2) + 4 * hi; }
; DI void dn_scan_item(const Params& p, int seqbase, int T, int h, int dir, char* lds) {
;     ...
;         const int cn = dir ? N - 1 - n : n; const size_t mrow0 = (size_t)(gch0 + cn) * 64;
; #pragma unroll
;         for (int pt = 0; pt < 2; ++pt)
; #pragma unroll
;             for (int i = 0; i < 16; ++i) {
;                 const int pi = pt * 32 + crow(i, hh), tl = dir ? 63 - pi : pi;
;                 Oout[(mrow0 + tl) * 512 + h * 128 + slab * 32 + r32] = f2bf(o[pt][i]);
;             }
	v_sub_u32_e32 v81, 44, v100
	v_cndmask_b32_e64 v80, v81, v80, s[2:3]
	v_ashrrev_i32_e32 v81, 31, v80
	v_lshlrev_b64 v[80:81], 10, v[80:81]
	v_cvt_pk_bf16_f32 v82, v91, s0
	v_lshl_add_u64 v[80:81], v[96:97], 0, v[80:81]
	global_store_short v[80:81], v82, off
	v_add_u32_e32 v80, 24, v100
	v_sub_u32_e32 v81, 39, v100
	v_cndmask_b32_e64 v80, v81, v80, s[2:3]
	v_ashrrev_i32_e32 v81, 31, v80
	v_lshlrev_b64 v[80:81], 10, v[80:81]
	v_cvt_pk_bf16_f32 v82, v92, s0
	v_lshl_add_u64 v[80:81], v[96:97], 0, v[80:81]
	global_store_short v[80:81], v82, off
	v_add_u32_e32 v80, 25, v100
	v_sub_u32_e32 v81, 38, v100
	v_cndmask_b32_e64 v80, v81, v80, s[2:3]
	v_ashrrev_i32_e32 v81, 31, v80
	v_lshlrev_b64 v[80:81], 10, v[80:81]
	v_cvt_pk_bf16_f32 v82, v93, s0
	v_lshl_add_u64 v[80:81], v[96:97], 0, v[80:81]
	global_store_short v[80:81], v82, off
	v_add_u32_e32 v80, 26, v100
	v_sub_u32_e32 v81, 37, v100
	v_cndmask_b32_e64 v80, v81, v80, s[2:3]
	v_ashrrev_i32_e32 v81, 31, v80
	v_lshlrev_b64 v[80:81], 10, v[80:81]
	v_cvt_pk_bf16_f32 v82, v94, s0
	v_lshl_add_u64 v[80:81], v[96:97], 0, v[80:81]
	global_store_short v[80:81], v82, off
	v_add_u32_e32 v80, 27, v100
	v_sub_u32_e32 v81, 36, v100
	v_cndmask_b32_e64 v80, v81, v80, s[2:3]
	v_ashrrev_i32_e32 v81, 31, v80
	v_lshlrev_b64 v[80:81], 10, v[80:81]
	v_cvt_pk_bf16_f32 v82, v95, s0
	v_lshl_add_u64 v[80:81], v[96:97], 0, v[80:81]
	global_store_short v[80:81], v82, off
	v_add_u32_e32 v80, 32, v100
	v_sub_u32_e32 v81, 31, v100
	v_cndmask_b32_e64 v80, v81, v80, s[2:3]
	v_ashrrev_i32_e32 v81, 31, v80
	v_lshlrev_b64 v[80:81], 10, v[80:81]
	v_lshl_add_u64 v[80:81], v[96:97], 0, v[80:81]
	global_store_short v[80:81], v64, off
	v_add_u32_e32 v64, 33, v100
	v_sub_u32_e32 v80, 30, v100
	v_cndmask_b32_e64 v64, v80, v64, s[2:3]
	v_cvt_pk_bf16_f32 v80, v65, s0
	v_ashrrev_i32_e32 v65, 31, v64
	v_lshlrev_b64 v[64:65], 10, v[64:65]
	v_lshl_add_u64 v[64:65], v[96:97], 0, v[64:65]
	global_store_short v[64:65], v80, off
	v_add_u32_e32 v64, 34, v100
	v_sub_u32_e32 v65, 29, v100
	v_cndmask_b32_e64 v64, v65, v64, s[2:3]
	v_ashrrev_i32_e32 v65, 31, v64
	v_lshlrev_b64 v[64:65], 10, v[64:65]
	v_lshl_add_u64 v[64:65], v[96:97], 0, v[64:65]
	global_store_short v[64:65], v66, off
	v_add_u32_e32 v64, 35, v100
	v_sub_u32_e32 v65, 28, v100
	v_cndmask_b32_e64 v64, v65, v64, s[2:3]
	v_ashrrev_i32_e32 v65, 31, v64
	v_lshlrev_b64 v[64:65], 10, v[64:65]
	v_cvt_pk_bf16_f32 v66, v67, s0
	v_lshl_add_u64 v[64:65], v[96:97], 0, v[64:65]
	global_store_short v[64:65], v66, off
	v_add_u32_e32 v64, 40, v100
	v_sub_u32_e32 v65, 23, v100
	v_cndmask_b32_e64 v64, v65, v64, s[2:3]
	v_ashrrev_i32_e32 v65, 31, v64
	v_lshlrev_b64 v[64:65], 10, v[64:65]
	v_cvt_pk_bf16_f32 v66, v68, s0
	v_lshl_add_u64 v[64:65], v[96:97], 0, v[64:65]
	global_store_short v[64:65], v66, off
	v_add_u32_e32 v64, 41, v100
	v_sub_u32_e32 v65, 22, v100
	v_cndmask_b32_e64 v64, v65, v64, s[2:3]
	v_ashrrev_i32_e32 v65, 31, v64
	v_lshlrev_b64 v[64:65], 10, v[64:65]
	v_cvt_pk_bf16_f32 v66, v69, s0
	v_lshl_add_u64 v[64:65], v[96:97], 0, v[64:65]
	global_store_short v[64:65], v66, off
	v_add_u32_e32 v64, 42, v100
	v_sub_u32_e32 v65, 21, v100
	v_cndmask_b32_e64 v64, v65, v64, s[2:3]
	v_ashrrev_i32_e32 v65, 31, v64
	v_lshlrev_b64 v[64:65], 10, v[64:65]
	v_cvt_pk_bf16_f32 v66, v70, s0
	v_lshl_add_u64 v[64:65], v[96:97], 0, v[64:65]
	global_store_short v[64:65], v66, off
	v_add_u32_e32 v64, 43, v100
	v_sub_u32_e32 v65, 20, v100
	v_cndmask_b32_e64 v64, v65, v64, s[2:3]
	v_ashrrev_i32_e32 v65, 31, v64
	v_lshlrev_b64 v[64:65], 10, v[64:65]
	v_cvt_pk_bf16_f32 v66, v71, s0
	v_lshl_add_u64 v[64:65], v[96:97], 0, v[64:65]
	global_store_short v[64:65], v66, off
	v_add_u32_e32 v64, 48, v100
	v_sub_u32_e32 v65, 15, v100
	v_cndmask_b32_e64 v64, v65, v64, s[2:3]
	v_ashrrev_i32_e32 v65, 31, v64
	v_lshlrev_b64 v[64:65], 10, v[64:65]
	v_cvt_pk_bf16_f32 v66, v72, s0
	v_lshl_add_u64 v[64:65], v[96:97], 0, v[64:65]
	global_store_short v[64:65], v66, off
	v_add_u32_e32 v64, 49, v100
	v_sub_u32_e32 v65, 14, v100
	v_cndmask_b32_e64 v64, v65, v64, s[2:3]
	v_ashrrev_i32_e32 v65, 31, v64
	v_lshlrev_b64 v[64:65], 10, v[64:65]
	v_cvt_pk_bf16_f32 v66, v73, s0
	v_lshl_add_u64 v[64:65], v[96:97], 0, v[64:65]
	global_store_short v[64:65], v66, off
	v_add_u32_e32 v64, 50, v100
	v_sub_u32_e32 v65, 13, v100
	v_cndmask_b32_e64 v64, v65, v64, s[2:3]
	v_ashrrev_i32_e32 v65, 31, v64
	v_lshlrev_b64 v[64:65], 10, v[64:65]
	v_cvt_pk_bf16_f32 v66, v74, s0
	v_lshl_add_u64 v[64:65], v[96:97], 0, v[64:65]
	global_store_short v[64:65], v66, off
	v_add_u32_e32 v64, 51, v100
	v_sub_u32_e32 v65, 12, v100
	v_cndmask_b32_e64 v64, v65, v64, s[2:3]
	v_ashrrev_i32_e32 v65, 31, v64
	v_lshlrev_b64 v[64:65], 10, v[64:65]
	v_cvt_pk_bf16_f32 v66, v75, s0
	v_lshl_add_u64 v[64:65], v[96:97], 0, v[64:65]
	global_store_short v[64:65], v66, off
	v_add_u32_e32 v64, 56, v100
	v_sub_u32_e32 v65, 7, v100
	v_cndmask_b32_e64 v64, v65, v64, s[2:3]
	v_ashrrev_i32_e32 v65, 31, v64
	v_lshlrev_b64 v[64:65], 10, v[64:65]
	v_cvt_pk_bf16_f32 v66, v76, s0
	v_lshl_add_u64 v[64:65], v[96:97], 0, v[64:65]
	global_store_short v[64:65], v66, off
	v_add_u32_e32 v64, 57, v100
	v_sub_u32_e32 v65, 6, v100
	v_cndmask_b32_e64 v64, v65, v64, s[2:3]
	v_ashrrev_i32_e32 v65, 31, v64
	v_lshlrev_b64 v[64:65], 10, v[64:65]
	v_cvt_pk_bf16_f32 v66, v77, s0
	v_lshl_add_u64 v[64:65], v[96:97], 0, v[64:65]
	global_store_short v[64:65], v66, off
	v_add_u32_e32 v64, 58, v100
	v_sub_u32_e32 v65, 5, v100
	v_cndmask_b32_e64 v64, v65, v64, s[2:3]
	v_ashrrev_i32_e32 v65, 31, v64
	v_lshlrev_b64 v[64:65], 10, v[64:65]
	v_cvt_pk_bf16_f32 v66, v78, s0
	v_lshl_add_u64 v[64:65], v[96:97], 0, v[64:65]
	global_store_short v[64:65], v66, off
	v_add_u32_e32 v64, 59, v100
	v_sub_u32_e32 v65, 4, v100
	v_cndmask_b32_e64 v64, v65, v64, s[2:3]
	v_ashrrev_i32_e32 v65, 31, v64
	v_lshlrev_b64 v[64:65], 10, v[64:65]
	v_cvt_pk_bf16_f32 v66, v79, s0
	v_lshl_add_u64 v[64:65], v[96:97], 0, v[64:65]
	v_mov_b64_e32 v[162:163], v[154:155]
	global_store_short v[64:65], v66, off
	v_mov_b32_e32 v64, v204
	v_mov_b64_e32 v[160:161], v[152:153]
	s_barrier
; DI void dn_scan_item(const Params& p, int seqbase, int T, int h, int dir, char* lds) {
;     ...
;     auto uload = [&](int n, URegs& U) {
;         int lane = lane0; asm volatile("" : "+v"(lane));
;         const int cn = dir ? N - 1 - n : n; const size_t ci = (size_t)((gch0 + cn) * 4 + h) * 2 + dir;
;         const bf16_t* Uc = UcB + ci * 8192;
; #pragma unroll
;         for (int pt = 0; pt < 2; ++pt) { const u32x4* sp = (const u32x4*)(Uc + ((slab * 2 + pt) * 64 + lane) * 16); U.un[pt][0] = sp[0]; U.un[pt][1] = sp[1]; }
;         U.gl = GcB[ci * 64 + 63];
;     };
;     ...
;         for (int n = 0; n < N; n += 2) {
;             compute(n, 0, UA);
;             __syncthreads();
;             compute(n + 1, 1, UB);
;             __syncthreads();
;         }
	s_cbranch_scc1 .LBB0_624
	s_add_i32 s21, s14, -3
	s_and_b64 s[22:23], s[2:3], exec
	s_cselect_b32 s21, s19, s21
	s_add_i32 s21, s21, s25
	s_lshl_b32 s21, s21, 2
	s_or_b32 s22, s21, s24
	s_ashr_i32 s23, s22, 31
	v_mov_b32_e32 v65, v204
	s_lshl_b64 s[22:23], s[22:23], 1
	s_or_b64 s[22:23], s[22:23], s[12:13]
	s_lshl_b64 s[26:27], s[22:23], 14
	v_lshlrev_b32_e32 v65, 4, v65
	s_add_u32 s26, s76, s26
	v_add_u32_e32 v66, s15, v65
	s_addc_u32 s27, s77, s27
	v_ashrrev_i32_e32 v67, 31, v66
	v_lshl_add_u64 v[66:67], v[66:67], 1, s[26:27]
	global_load_dwordx4 v[160:163], v[66:67], off offset:16
	global_load_dwordx4 v[164:167], v[66:67], off
	v_add_u32_e32 v66, s16, v65
	s_lshl_b64 s[22:23], s[22:23], 8
	v_ashrrev_i32_e32 v67, 31, v66
	s_add_u32 s22, s78, s22
	v_lshl_add_u64 v[66:67], v[66:67], 1, s[26:27]
	s_addc_u32 s23, s79, s23
	global_load_dwordx4 v[168:171], v[66:67], off offset:16
	global_load_dwordx4 v[172:175], v[66:67], off
	global_load_dword v207, v185, s[22:23] offset:252
	s_branch .LBB0_624
